# gate GEMM epilogue list-scheduled row by row: its 8 dwordx4 stores issue as each row is packed instead of in a burst at the end (pure reorder, both layers)
# speedup vs baseline: 1.0098x; 1.0098x over previous
;     __device__ __forceinline__ void operator()(const f32x4 (&acc)[2][2][4][2], const Unit& u, int wr, int wc, int fr, int fq) const {
;         asm volatile("" : "+v"(fr), "+v"(fq));
;         const int row0 = u.pm * BM + wr * 64 + fr, col0 = u.pn * BM + wc * 64 + 16 * fq;
;         const int gn = u.pn >> 2, gbase = (gn < 3) ? 3072 + 1024 * gn : 0;
;         f32x4 bv[2][2];
; #pragma unroll
;         for (int bj = 0; bj < 2; ++bj)
; #pragma unroll
;             for (int n = 0; n < 2; ++n) bv[bj][n] = *(const f32x4*)(bias + col0 + 8 * bj + 4 * n) * -1.44269504f;
;         f32x4 wv[2][2];
; #pragma unroll
;         for (int bj = 0; bj < 2; ++bj)
; #pragma unroll
;             for (int n = 0; n < 2; ++n) wv[bj][n] = *(const f32x4*)(SW + col0 + 8 * bj + 4 * n) * -1.44269504f;
;         float rsv[8];
; #pragma unroll
;         for (int i = 0; i < 8; ++i) rsv[i] = SH[row0 + (i >> 2) * HALF + (i & 3) * 16];
;     ...
; #pragma unroll
;         for (int ai = 0; ai < 2; ++ai)
; #pragma unroll
;             for (int m = 0; m < 4; ++m) { unsigned char* rowp = O + (size_t)(row0 + ai * HALF + m * 16) * 8704 + gbase + (col0 & 1023);
;                 const float rs = rsv[ai * 4 + m];
;                 u32x4 w; EPG_Q4(w.x, acc[ai][0][m][0], wv[0][0], rs, bv[0][0]); EPG_Q4(w.y, acc[ai][0][m][1], wv[0][1], rs, bv[0][1]);
;                 EPG_Q4(w.z, acc[ai][1][m][0], wv[1][0], rs, bv[1][0]); EPG_Q4(w.w, acc[ai][1][m][1], wv[1][1], rs, bv[1][1]);
;                 *(u32x4*)rowp = w; }
.LBB0_1195:
	s_lshl_b32 s0, s59, 8
	v_mov_b32_e32 v130, v179
	v_mov_b32_e32 v154, v1
	s_or_b32 s0, s0, s53
	v_cvt_f32_i32_e32 v212, v122
	v_lshl_add_u32 v144, v130, 4, s0
	s_lshl_b32 s0, s38, 8
	v_ashrrev_i32_e32 v145, 31, v144
	s_add_i32 s0, s0, s50
	v_lshlrev_b64 v[142:143], 2, v[144:145]
	v_add_u32_e32 v164, s0, v154
	v_lshl_add_u64 v[160:161], s[10:11], 0, v[142:143]
	v_ashrrev_i32_e32 v165, 31, v164
	global_load_dwordx4 v[130:133], v[160:161], off
	global_load_dwordx4 v[134:137], v[160:161], off offset:16
	global_load_dwordx4 v[138:141], v[160:161], off offset:32
	s_nop 0
	global_load_dwordx4 v[160:163], v[160:161], off offset:48
	v_lshl_add_u64 v[142:143], s[14:15], 0, v[142:143]
	v_lshl_add_u64 v[170:171], v[164:165], 2, s[16:17]
	global_load_dwordx4 v[166:169], v[142:143], off
	global_load_dwordx4 v[194:197], v[142:143], off offset:16
	global_load_dwordx4 v[198:201], v[142:143], off offset:32
	global_load_dwordx4 v[202:205], v[142:143], off offset:48
	global_load_dword v206, v[170:171], off
	global_load_dword v188, v[170:171], off offset:64
	global_load_dword v186, v[170:171], off offset:128
	global_load_dword v184, v[170:171], off offset:192
	global_load_dword v182, v[170:171], off offset:512
	global_load_dword v180, v[170:171], off offset:576
	global_load_dword v178, v[170:171], off offset:640
	global_load_dword v122, v[170:171], off offset:704
	s_ashr_i32 s0, s59, 2
	s_lshl_b32 s1, s0, 10
	v_mov_b64_e32 v[142:143], s[12:13]
	s_add_i32 s2, s1, 0xc00
	v_cvt_f32_i32_e32 v209, v127
	v_cvt_f32_i32_e32 v208, v126
	v_cvt_f32_i32_e32 v215, v125
	v_cvt_f32_i32_e32 v214, v124
	s_cmp_lt_i32 s0, 3
	v_mad_i64_i32 v[124:125], s[0:1], v164, s57, v[142:143]
	s_cselect_b32 s0, s2, 0
	v_cvt_f32_i32_e32 v211, v129
	v_cvt_f32_i32_e32 v210, v128
	s_ashr_i32 s1, s0, 31
	v_cvt_f32_i32_e32 v115, v115
	v_cvt_f32_i32_e32 v114, v114
	v_cvt_f32_i32_e32 v99, v99
	v_cvt_f32_i32_e32 v98, v98
	v_cvt_f32_i32_e32 v83, v83
	v_cvt_f32_i32_e32 v82, v82
	v_cvt_f32_i32_e32 v67, v67
	v_cvt_f32_i32_e32 v66, v66
	v_cvt_f32_i32_e32 v51, v51
	v_cvt_f32_i32_e32 v50, v50
	v_cvt_f32_i32_e32 v35, v35
	v_cvt_f32_i32_e32 v34, v34
	v_cvt_f32_i32_e32 v19, v19
	v_cvt_f32_i32_e32 v18, v18
	v_and_b32_e32 v154, 0x3f0, v144
	v_lshl_add_u64 v[124:125], v[124:125], 0, s[0:1]
	v_cvt_f32_i32_e32 v117, v117
	v_cvt_f32_i32_e32 v116, v116
	v_cvt_f32_i32_e32 v111, v111
	v_cvt_f32_i32_e32 v110, v110
	v_cvt_f32_i32_e32 v101, v101
	v_cvt_f32_i32_e32 v100, v100
	v_cvt_f32_i32_e32 v95, v95
	v_cvt_f32_i32_e32 v94, v94
	v_cvt_f32_i32_e32 v85, v85
	v_cvt_f32_i32_e32 v84, v84
	v_cvt_f32_i32_e32 v79, v79
	v_cvt_f32_i32_e32 v78, v78
	v_cvt_f32_i32_e32 v69, v69
	v_cvt_f32_i32_e32 v68, v68
	v_cvt_f32_i32_e32 v63, v63
	v_cvt_f32_i32_e32 v62, v62
	v_cvt_f32_i32_e32 v53, v53
	v_cvt_f32_i32_e32 v52, v52
	v_cvt_f32_i32_e32 v47, v47
	v_cvt_f32_i32_e32 v46, v46
	v_cvt_f32_i32_e32 v37, v37
	v_cvt_f32_i32_e32 v36, v36
	v_cvt_f32_i32_e32 v31, v31
	v_cvt_f32_i32_e32 v30, v30
	v_cvt_f32_i32_e32 v21, v21
	v_cvt_f32_i32_e32 v20, v20
	v_cvt_f32_i32_e32 v15, v15
	v_cvt_f32_i32_e32 v14, v14
	v_add_u32_e32 v207, 32, v164
	v_lshl_add_u64 v[216:217], v[124:125], 0, v[154:155]
	v_add_u32_e32 v189, 0xa0, v164
	v_cvt_f32_i32_e32 v213, v123
	v_add_u32_e32 v123, 0xb0, v164
	v_cvt_f32_i32_e32 v119, v119
	v_cvt_f32_i32_e32 v118, v118
	v_cvt_f32_i32_e32 v109, v109
	v_cvt_f32_i32_e32 v108, v108
	v_cvt_f32_i32_e32 v103, v103
	v_cvt_f32_i32_e32 v102, v102
	v_cvt_f32_i32_e32 v93, v93
	s_waitcnt vmcnt(0)
	v_pk_mul_f32 v[172:173], v[130:131], s[22:23] op_sel_hi:[1,0]
	v_pk_mul_f32 v[170:171], v[132:133], s[22:23] op_sel_hi:[1,0]
	v_pk_mul_f32 v[174:175], v[166:167], s[22:23] op_sel_hi:[1,0]
	v_pk_mul_f32 v[124:125], v[162:163], s[22:23] op_sel_hi:[1,0]
	v_pk_mul_f32 v[162:163], v[174:175], v[208:209]
	v_pk_mul_f32 v[176:177], v[168:169], s[22:23] op_sel_hi:[1,0]
	v_pk_mul_f32 v[130:131], v[202:203], s[22:23] op_sel_hi:[1,0]
	v_pk_fma_f32 v[162:163], v[162:163], v[206:207], v[172:173] op_sel_hi:[1,0,1]
	v_pk_mul_f32 v[128:129], v[160:161], s[22:23] op_sel_hi:[1,0]
	v_pk_mul_f32 v[132:133], v[204:205], s[22:23] op_sel_hi:[1,0]
	v_pk_mul_f32 v[160:161], v[176:177], v[210:211]
	v_exp_f32_e32 v162, v162
	v_exp_f32_e32 v163, v163
	v_pk_mul_f32 v[114:115], v[130:131], v[114:115]
	v_pk_fma_f32 v[160:161], v[160:161], v[206:207], v[170:171] op_sel_hi:[1,0,1]
	v_pk_mul_f32 v[116:117], v[132:133], v[116:117]
	v_pk_fma_f32 v[114:115], v[114:115], v[206:207], v[128:129] op_sel_hi:[1,0,1]
	v_exp_f32_e32 v160, v160
	v_exp_f32_e32 v161, v161
	v_pk_fma_f32 v[116:117], v[116:117], v[206:207], v[124:125] op_sel_hi:[1,0,1]
	v_exp_f32_e32 v114, v114
	v_exp_f32_e32 v115, v115
	v_cvt_f32_i32_e32 v121, v121
	v_cvt_f32_i32_e32 v120, v120
	v_exp_f32_e32 v116, v116
	v_exp_f32_e32 v117, v117
	v_pk_mul_f32 v[166:167], v[194:195], s[22:23] op_sel_hi:[1,0]
	v_pk_add_f32 v[162:163], v[162:163], 1.0 op_sel_hi:[1,0]
	v_add_u32_e32 v193, 16, v164
	v_add_u32_e32 v192, 48, v164
	v_add_u32_e32 v191, 0x80, v164
	v_add_u32_e32 v190, 0x90, v164
	v_pk_mul_f32 v[144:145], v[136:137], s[22:23] op_sel_hi:[1,0]
	v_pk_mul_f32 v[164:165], v[134:135], s[22:23] op_sel_hi:[1,0]
	v_pk_mul_f32 v[136:137], v[138:139], s[22:23] op_sel_hi:[1,0]
	v_pk_mul_f32 v[168:169], v[196:197], s[22:23] op_sel_hi:[1,0]
	v_pk_mul_f32 v[138:139], v[198:199], s[22:23] op_sel_hi:[1,0]
	v_pk_mul_f32 v[196:197], v[166:167], v[212:213]
	v_rcp_f32_e32 v162, v162
	v_rcp_f32_e32 v163, v163
	v_pk_mul_f32 v[134:135], v[140:141], s[22:23] op_sel_hi:[1,0]
	v_pk_mul_f32 v[140:141], v[200:201], s[22:23] op_sel_hi:[1,0]
	v_pk_mul_f32 v[194:195], v[168:169], v[214:215]
	v_pk_fma_f32 v[196:197], v[196:197], v[206:207], v[164:165] op_sel_hi:[1,0,1]
;     __device__ __forceinline__ void operator()(const f32x4 (&acc)[2][2][4][2], const Unit& u, int wr, int wc, int fr, int fq) const {
;     ...
; #pragma unroll
;         for (int ai = 0; ai < 2; ++ai)
; #pragma unroll
;             for (int m = 0; m < 4; ++m) { unsigned char* rowp = O + (size_t)(row0 + ai * HALF + m * 16) * 8704 + gbase + (col0 & 1023);
;                 const float rs = rsv[ai * 4 + m];
;                 u32x4 w; EPG_Q4(w.x, acc[ai][0][m][0], wv[0][0], rs, bv[0][0]); EPG_Q4(w.y, acc[ai][0][m][1], wv[0][1], rs, bv[0][1]);
;                 EPG_Q4(w.z, acc[ai][1][m][0], wv[1][0], rs, bv[1][0]); EPG_Q4(w.w, acc[ai][1][m][1], wv[1][1], rs, bv[1][1]);
;                 *(u32x4*)rowp = w; }
	v_pk_add_f32 v[160:161], v[160:161], 1.0 op_sel_hi:[1,0]
	v_pk_mul_f32 v[118:119], v[138:139], v[118:119]
	v_pk_add_f32 v[114:115], v[114:115], 1.0 op_sel_hi:[1,0]
	v_pk_fma_f32 v[194:195], v[194:195], v[206:207], v[144:145] op_sel_hi:[1,0,1]
	v_exp_f32_e32 v196, v196
	v_rcp_f32_e32 v160, v160
	v_rcp_f32_e32 v161, v161
	v_exp_f32_e32 v197, v197
	v_pk_mul_f32 v[120:121], v[140:141], v[120:121]
	v_pk_fma_f32 v[118:119], v[118:119], v[206:207], v[136:137] op_sel_hi:[1,0,1]
	v_pk_add_f32 v[116:117], v[116:117], 1.0 op_sel_hi:[1,0]
	v_rcp_f32_e32 v114, v114
	v_rcp_f32_e32 v115, v115
	v_mov_b64_e32 v[126:127], s[24:25]
	v_exp_f32_e32 v194, v194
	v_exp_f32_e32 v195, v195
	v_pk_fma_f32 v[120:121], v[120:121], v[206:207], v[134:135] op_sel_hi:[1,0,1]
	v_exp_f32_e32 v118, v118
	v_exp_f32_e32 v119, v119
	v_rcp_f32_e32 v116, v116
	v_rcp_f32_e32 v117, v117
	v_pk_fma_f32 v[162:163], v[162:163], s[26:27], v[126:127] op_sel_hi:[1,0,0]
	v_exp_f32_e32 v120, v120
	v_exp_f32_e32 v121, v121
	v_max_f32_e32 v163, 0x4b000001, v163
	v_max_f32_e32 v162, 0x4b000001, v162
	v_pk_fma_f32 v[160:161], v[160:161], s[26:27], v[126:127] op_sel_hi:[1,0,0]
	v_perm_b32 v198, v163, v162, s58
	v_pk_add_f32 v[162:163], v[196:197], 1.0 op_sel_hi:[1,0]
	v_pk_fma_f32 v[114:115], v[114:115], s[26:27], v[126:127] op_sel_hi:[1,0,0]
	v_max_f32_e32 v199, 0x4b000001, v161
	v_max_f32_e32 v200, 0x4b000001, v160
	v_pk_add_f32 v[160:161], v[194:195], 1.0 op_sel_hi:[1,0]
	v_rcp_f32_e32 v162, v162
	v_rcp_f32_e32 v163, v163
	v_pk_add_f32 v[118:119], v[118:119], 1.0 op_sel_hi:[1,0]
	v_pk_fma_f32 v[116:117], v[116:117], s[26:27], v[126:127] op_sel_hi:[1,0,0]
	v_max_f32_e32 v115, 0x4b000001, v115
	v_max_f32_e32 v114, 0x4b000001, v114
	v_rcp_f32_e32 v194, v160
	v_rcp_f32_e32 v195, v161
	v_pk_add_f32 v[120:121], v[120:121], 1.0 op_sel_hi:[1,0]
	v_rcp_f32_e32 v118, v118
	v_rcp_f32_e32 v119, v119
	v_perm_b32 v114, v115, v114, s58
	v_max_f32_e32 v115, 0x4b000001, v117
	v_max_f32_e32 v116, 0x4b000001, v116
	v_rcp_f32_e32 v120, v120
	v_rcp_f32_e32 v121, v121
	v_perm_b32 v115, v115, v116, s58
	v_pk_fma_f32 v[162:163], v[162:163], s[26:27], v[126:127] op_sel_hi:[1,0,0]
	v_pk_fma_f32 v[194:195], v[194:195], s[26:27], v[126:127] op_sel_hi:[1,0,0]
	v_max_f32_e32 v161, 0x4b000001, v163
	v_max_f32_e32 v162, 0x4b000001, v162
	v_pk_fma_f32 v[118:119], v[118:119], s[26:27], v[126:127] op_sel_hi:[1,0,0]
	v_perm_b32 v161, v161, v162, s58
	v_max_f32_e32 v162, 0x4b000001, v195
	v_max_f32_e32 v163, 0x4b000001, v194
	v_pk_fma_f32 v[120:121], v[120:121], s[26:27], v[126:127] op_sel_hi:[1,0,0]
	v_max_f32_e32 v119, 0x4b000001, v119
	v_max_f32_e32 v118, 0x4b000001, v118
	v_perm_b32 v162, v162, v163, s58
	v_perm_b32 v118, v119, v118, s58
	v_max_f32_e32 v119, 0x4b000001, v121
	v_max_f32_e32 v120, 0x4b000001, v120
	v_lshl_or_b32 v163, v115, 16, v114
	v_perm_b32 v160, v199, v200, s58
	v_perm_b32 v119, v119, v120, s58
	v_lshl_or_b32 v160, v160, 16, v198
	v_lshl_or_b32 v161, v162, 16, v161
	v_lshl_or_b32 v162, v119, 16, v118
	global_store_dwordx4 v[216:217], v[160:163], off
	v_pk_mul_f32 v[98:99], v[130:131], v[98:99]
	v_pk_mul_f32 v[110:111], v[174:175], v[110:111]
	v_pk_mul_f32 v[100:101], v[132:133], v[100:101]
	v_pk_fma_f32 v[98:99], v[98:99], v[188:189], v[128:129] op_sel_hi:[1,0,1]
	v_pk_fma_f32 v[110:111], v[110:111], v[188:189], v[172:173] op_sel_hi:[1,0,1]
	v_pk_fma_f32 v[100:101], v[100:101], v[188:189], v[124:125] op_sel_hi:[1,0,1]
	v_exp_f32_e32 v98, v98
	v_exp_f32_e32 v99, v99
	v_cvt_f32_i32_e32 v113, v113
	v_cvt_f32_i32_e32 v112, v112
	v_exp_f32_e32 v110, v110
	v_exp_f32_e32 v111, v111
	v_cvt_f32_i32_e32 v107, v107
	v_cvt_f32_i32_e32 v106, v106
	v_cvt_f32_i32_e32 v105, v105
	v_cvt_f32_i32_e32 v104, v104
	v_exp_f32_e32 v100, v100
	v_exp_f32_e32 v101, v101
	v_pk_mul_f32 v[108:109], v[168:169], v[108:109]
	v_pk_mul_f32 v[102:103], v[138:139], v[102:103]
	v_pk_add_f32 v[98:99], v[98:99], 1.0 op_sel_hi:[1,0]
	v_pk_mul_f32 v[112:113], v[176:177], v[112:113]
	v_pk_add_f32 v[110:111], v[110:111], 1.0 op_sel_hi:[1,0]
	v_pk_mul_f32 v[106:107], v[166:167], v[106:107]
	v_pk_fma_f32 v[108:109], v[108:109], v[188:189], v[144:145] op_sel_hi:[1,0,1]
	v_pk_mul_f32 v[104:105], v[140:141], v[104:105]
	v_pk_fma_f32 v[102:103], v[102:103], v[188:189], v[136:137] op_sel_hi:[1,0,1]
	v_pk_add_f32 v[100:101], v[100:101], 1.0 op_sel_hi:[1,0]
	v_rcp_f32_e32 v98, v98
	v_rcp_f32_e32 v99, v99
	v_pk_fma_f32 v[112:113], v[112:113], v[188:189], v[170:171] op_sel_hi:[1,0,1]
	v_rcp_f32_e32 v110, v110
	v_rcp_f32_e32 v111, v111
	v_pk_fma_f32 v[106:107], v[106:107], v[188:189], v[164:165] op_sel_hi:[1,0,1]
	v_exp_f32_e32 v108, v108
	v_exp_f32_e32 v109, v109
	v_pk_fma_f32 v[104:105], v[104:105], v[188:189], v[134:135] op_sel_hi:[1,0,1]
	v_exp_f32_e32 v102, v102
	v_exp_f32_e32 v103, v103
	v_rcp_f32_e32 v100, v100
	v_rcp_f32_e32 v101, v101
	v_exp_f32_e32 v112, v112
	v_exp_f32_e32 v113, v113
	v_exp_f32_e32 v106, v106
	v_exp_f32_e32 v107, v107
	v_exp_f32_e32 v104, v104
	v_exp_f32_e32 v105, v105
	v_pk_fma_f32 v[98:99], v[98:99], s[26:27], v[126:127] op_sel_hi:[1,0,0]
	v_pk_fma_f32 v[110:111], v[110:111], s[26:27], v[126:127] op_sel_hi:[1,0,0]
	v_pk_add_f32 v[108:109], v[108:109], 1.0 op_sel_hi:[1,0]
	v_pk_add_f32 v[102:103], v[102:103], 1.0 op_sel_hi:[1,0]
	v_pk_fma_f32 v[100:101], v[100:101], s[26:27], v[126:127] op_sel_hi:[1,0,0]
	v_max_f32_e32 v99, 0x4b000001, v99
	v_max_f32_e32 v98, 0x4b000001, v98
	v_pk_add_f32 v[112:113], v[112:113], 1.0 op_sel_hi:[1,0]
	v_max_f32_e32 v111, 0x4b000001, v111
	v_max_f32_e32 v110, 0x4b000001, v110
	v_pk_add_f32 v[106:107], v[106:107], 1.0 op_sel_hi:[1,0]
	v_rcp_f32_e32 v108, v108
	v_rcp_f32_e32 v109, v109
;     __device__ __forceinline__ void operator()(const f32x4 (&acc)[2][2][4][2], const Unit& u, int wr, int wc, int fr, int fq) const {
;     ...
; #pragma unroll
;         for (int ai = 0; ai < 2; ++ai)
; #pragma unroll
;             for (int m = 0; m < 4; ++m) { unsigned char* rowp = O + (size_t)(row0 + ai * HALF + m * 16) * 8704 + gbase + (col0 & 1023);
;                 const float rs = rsv[ai * 4 + m];
;                 u32x4 w; EPG_Q4(w.x, acc[ai][0][m][0], wv[0][0], rs, bv[0][0]); EPG_Q4(w.y, acc[ai][0][m][1], wv[0][1], rs, bv[0][1]);
;                 EPG_Q4(w.z, acc[ai][1][m][0], wv[1][0], rs, bv[1][0]); EPG_Q4(w.w, acc[ai][1][m][1], wv[1][1], rs, bv[1][1]);
;                 *(u32x4*)rowp = w; }
	v_pk_add_f32 v[104:105], v[104:105], 1.0 op_sel_hi:[1,0]
	v_rcp_f32_e32 v102, v102
	v_rcp_f32_e32 v103, v103
	v_perm_b32 v98, v99, v98, s58
	v_max_f32_e32 v99, 0x4b000001, v101
	v_max_f32_e32 v100, 0x4b000001, v100
	v_rcp_f32_e32 v112, v112
	v_rcp_f32_e32 v113, v113
	v_perm_b32 v116, v111, v110, s58
	v_rcp_f32_e32 v110, v106
	v_rcp_f32_e32 v111, v107
	v_rcp_f32_e32 v104, v104
	v_rcp_f32_e32 v105, v105
	v_perm_b32 v99, v99, v100, s58
	v_pk_fma_f32 v[108:109], v[108:109], s[26:27], v[126:127] op_sel_hi:[1,0,0]
	v_pk_fma_f32 v[102:103], v[102:103], s[26:27], v[126:127] op_sel_hi:[1,0,0]
	v_pk_fma_f32 v[112:113], v[112:113], s[26:27], v[126:127] op_sel_hi:[1,0,0]
	v_pk_fma_f32 v[110:111], v[110:111], s[26:27], v[126:127] op_sel_hi:[1,0,0]
	v_max_f32_e32 v109, 0x4b000001, v109
	v_max_f32_e32 v108, 0x4b000001, v108
	v_pk_fma_f32 v[104:105], v[104:105], s[26:27], v[126:127] op_sel_hi:[1,0,0]
	v_max_f32_e32 v103, 0x4b000001, v103
	v_max_f32_e32 v102, 0x4b000001, v102
	v_mad_i64_i32 v[114:115], s[2:3], v193, s57, v[142:143]
	v_max_f32_e32 v113, 0x4b000001, v113
	v_max_f32_e32 v112, 0x4b000001, v112
	v_max_f32_e32 v107, 0x4b000001, v111
	v_max_f32_e32 v110, 0x4b000001, v110
	v_perm_b32 v108, v109, v108, s58
	v_perm_b32 v102, v103, v102, s58
	v_max_f32_e32 v103, 0x4b000001, v105
	v_max_f32_e32 v104, 0x4b000001, v104
	v_lshl_or_b32 v109, v99, 16, v98
	v_lshl_add_u64 v[114:115], v[114:115], 0, s[0:1]
	v_perm_b32 v106, v113, v112, s58
	v_perm_b32 v107, v107, v110, s58
	v_perm_b32 v103, v103, v104, s58
	v_lshl_add_u64 v[114:115], v[114:115], 0, v[154:155]
	v_lshl_or_b32 v106, v106, 16, v116
	v_lshl_or_b32 v107, v108, 16, v107
	v_lshl_or_b32 v108, v103, 16, v102
	global_store_dwordx4 v[114:115], v[106:109], off
	v_cvt_f32_i32_e32 v92, v92
	v_pk_mul_f32 v[82:83], v[130:131], v[82:83]
	v_pk_mul_f32 v[94:95], v[174:175], v[94:95]
	v_pk_mul_f32 v[84:85], v[132:133], v[84:85]
	v_pk_fma_f32 v[82:83], v[82:83], v[186:187], v[128:129] op_sel_hi:[1,0,1]
	v_pk_fma_f32 v[94:95], v[94:95], v[186:187], v[172:173] op_sel_hi:[1,0,1]
	v_cvt_f32_i32_e32 v87, v87
	v_cvt_f32_i32_e32 v86, v86
	v_pk_fma_f32 v[84:85], v[84:85], v[186:187], v[124:125] op_sel_hi:[1,0,1]
	v_exp_f32_e32 v82, v82
	v_exp_f32_e32 v83, v83
	v_cvt_f32_i32_e32 v97, v97
	v_cvt_f32_i32_e32 v96, v96
	v_exp_f32_e32 v94, v94
	v_exp_f32_e32 v95, v95
	v_cvt_f32_i32_e32 v91, v91
	v_cvt_f32_i32_e32 v90, v90
	v_cvt_f32_i32_e32 v89, v89
	v_cvt_f32_i32_e32 v88, v88
	v_exp_f32_e32 v84, v84
	v_exp_f32_e32 v85, v85
	v_pk_mul_f32 v[92:93], v[168:169], v[92:93]
	v_pk_mul_f32 v[86:87], v[138:139], v[86:87]
	v_pk_add_f32 v[82:83], v[82:83], 1.0 op_sel_hi:[1,0]
	v_pk_mul_f32 v[96:97], v[176:177], v[96:97]
	v_pk_add_f32 v[94:95], v[94:95], 1.0 op_sel_hi:[1,0]
	v_pk_mul_f32 v[90:91], v[166:167], v[90:91]
	v_pk_fma_f32 v[92:93], v[92:93], v[186:187], v[144:145] op_sel_hi:[1,0,1]
	v_pk_mul_f32 v[88:89], v[140:141], v[88:89]
	v_pk_fma_f32 v[86:87], v[86:87], v[186:187], v[136:137] op_sel_hi:[1,0,1]
	v_pk_add_f32 v[84:85], v[84:85], 1.0 op_sel_hi:[1,0]
	v_rcp_f32_e32 v82, v82
	v_rcp_f32_e32 v83, v83
	v_pk_fma_f32 v[96:97], v[96:97], v[186:187], v[170:171] op_sel_hi:[1,0,1]
	v_rcp_f32_e32 v94, v94
	v_rcp_f32_e32 v95, v95
	v_pk_fma_f32 v[90:91], v[90:91], v[186:187], v[164:165] op_sel_hi:[1,0,1]
	v_exp_f32_e32 v92, v92
	v_exp_f32_e32 v93, v93
	v_pk_fma_f32 v[88:89], v[88:89], v[186:187], v[134:135] op_sel_hi:[1,0,1]
	v_exp_f32_e32 v86, v86
	v_exp_f32_e32 v87, v87
	v_rcp_f32_e32 v84, v84
	v_rcp_f32_e32 v85, v85
	v_exp_f32_e32 v96, v96
	v_exp_f32_e32 v97, v97
	v_exp_f32_e32 v90, v90
	v_exp_f32_e32 v91, v91
	v_exp_f32_e32 v88, v88
	v_exp_f32_e32 v89, v89
	v_pk_fma_f32 v[82:83], v[82:83], s[26:27], v[126:127] op_sel_hi:[1,0,0]
	v_pk_fma_f32 v[94:95], v[94:95], s[26:27], v[126:127] op_sel_hi:[1,0,0]
	v_pk_add_f32 v[92:93], v[92:93], 1.0 op_sel_hi:[1,0]
	v_pk_add_f32 v[86:87], v[86:87], 1.0 op_sel_hi:[1,0]
	v_pk_fma_f32 v[84:85], v[84:85], s[26:27], v[126:127] op_sel_hi:[1,0,0]
	v_max_f32_e32 v83, 0x4b000001, v83
	v_max_f32_e32 v82, 0x4b000001, v82
	v_pk_add_f32 v[96:97], v[96:97], 1.0 op_sel_hi:[1,0]
	v_max_f32_e32 v95, 0x4b000001, v95
	v_max_f32_e32 v94, 0x4b000001, v94
	v_pk_add_f32 v[90:91], v[90:91], 1.0 op_sel_hi:[1,0]
	v_rcp_f32_e32 v92, v92
	v_rcp_f32_e32 v93, v93
	v_pk_add_f32 v[88:89], v[88:89], 1.0 op_sel_hi:[1,0]
	v_rcp_f32_e32 v86, v86
	v_rcp_f32_e32 v87, v87
	v_perm_b32 v82, v83, v82, s58
	v_max_f32_e32 v83, 0x4b000001, v85
	v_max_f32_e32 v84, 0x4b000001, v84
	v_rcp_f32_e32 v96, v96
	v_rcp_f32_e32 v97, v97
	v_perm_b32 v100, v95, v94, s58
	v_rcp_f32_e32 v94, v90
	v_rcp_f32_e32 v95, v91
	v_rcp_f32_e32 v88, v88
	v_rcp_f32_e32 v89, v89
	v_perm_b32 v83, v83, v84, s58
	v_pk_fma_f32 v[92:93], v[92:93], s[26:27], v[126:127] op_sel_hi:[1,0,0]
	v_pk_fma_f32 v[86:87], v[86:87], s[26:27], v[126:127] op_sel_hi:[1,0,0]
	v_pk_fma_f32 v[96:97], v[96:97], s[26:27], v[126:127] op_sel_hi:[1,0,0]
	v_pk_fma_f32 v[94:95], v[94:95], s[26:27], v[126:127] op_sel_hi:[1,0,0]
	v_max_f32_e32 v93, 0x4b000001, v93
	v_max_f32_e32 v92, 0x4b000001, v92
	v_pk_fma_f32 v[88:89], v[88:89], s[26:27], v[126:127] op_sel_hi:[1,0,0]
	v_max_f32_e32 v87, 0x4b000001, v87
	v_max_f32_e32 v86, 0x4b000001, v86
	v_mad_i64_i32 v[98:99], s[2:3], v207, s57, v[142:143]
	v_max_f32_e32 v97, 0x4b000001, v97
	v_max_f32_e32 v96, 0x4b000001, v96
	v_max_f32_e32 v91, 0x4b000001, v95
	v_max_f32_e32 v94, 0x4b000001, v94
	v_perm_b32 v92, v93, v92, s58
	v_perm_b32 v86, v87, v86, s58
	v_max_f32_e32 v87, 0x4b000001, v89
	v_max_f32_e32 v88, 0x4b000001, v88
	v_lshl_or_b32 v93, v83, 16, v82
	v_lshl_add_u64 v[98:99], v[98:99], 0, s[0:1]
	v_perm_b32 v90, v97, v96, s58
	v_perm_b32 v91, v91, v94, s58
;     __device__ __forceinline__ void operator()(const f32x4 (&acc)[2][2][4][2], const Unit& u, int wr, int wc, int fr, int fq) const {
;     ...
; #pragma unroll
;         for (int ai = 0; ai < 2; ++ai)
; #pragma unroll
;             for (int m = 0; m < 4; ++m) { unsigned char* rowp = O + (size_t)(row0 + ai * HALF + m * 16) * 8704 + gbase + (col0 & 1023);
;                 const float rs = rsv[ai * 4 + m];
;                 u32x4 w; EPG_Q4(w.x, acc[ai][0][m][0], wv[0][0], rs, bv[0][0]); EPG_Q4(w.y, acc[ai][0][m][1], wv[0][1], rs, bv[0][1]);
;                 EPG_Q4(w.z, acc[ai][1][m][0], wv[1][0], rs, bv[1][0]); EPG_Q4(w.w, acc[ai][1][m][1], wv[1][1], rs, bv[1][1]);
;                 *(u32x4*)rowp = w; }
	v_perm_b32 v87, v87, v88, s58
	v_lshl_add_u64 v[98:99], v[98:99], 0, v[154:155]
	v_lshl_or_b32 v90, v90, 16, v100
	v_lshl_or_b32 v91, v92, 16, v91
	v_lshl_or_b32 v92, v87, 16, v86
	global_store_dwordx4 v[98:99], v[90:93], off
	v_pk_mul_f32 v[66:67], v[130:131], v[66:67]
	v_pk_mul_f32 v[78:79], v[174:175], v[78:79]
	v_pk_mul_f32 v[68:69], v[132:133], v[68:69]
	v_pk_fma_f32 v[66:67], v[66:67], v[184:185], v[128:129] op_sel_hi:[1,0,1]
	v_pk_fma_f32 v[78:79], v[78:79], v[184:185], v[172:173] op_sel_hi:[1,0,1]
	v_cvt_f32_i32_e32 v77, v77
	v_cvt_f32_i32_e32 v76, v76
	v_cvt_f32_i32_e32 v71, v71
	v_cvt_f32_i32_e32 v70, v70
	v_pk_fma_f32 v[68:69], v[68:69], v[184:185], v[124:125] op_sel_hi:[1,0,1]
	v_exp_f32_e32 v66, v66
	v_exp_f32_e32 v67, v67
	v_cvt_f32_i32_e32 v81, v81
	v_cvt_f32_i32_e32 v80, v80
	v_exp_f32_e32 v78, v78
	v_exp_f32_e32 v79, v79
	v_cvt_f32_i32_e32 v75, v75
	v_cvt_f32_i32_e32 v74, v74
	v_cvt_f32_i32_e32 v73, v73
	v_cvt_f32_i32_e32 v72, v72
	v_exp_f32_e32 v68, v68
	v_exp_f32_e32 v69, v69
	v_pk_mul_f32 v[76:77], v[168:169], v[76:77]
	v_pk_mul_f32 v[70:71], v[138:139], v[70:71]
	v_pk_add_f32 v[66:67], v[66:67], 1.0 op_sel_hi:[1,0]
	v_pk_mul_f32 v[80:81], v[176:177], v[80:81]
	v_pk_add_f32 v[78:79], v[78:79], 1.0 op_sel_hi:[1,0]
	v_pk_mul_f32 v[74:75], v[166:167], v[74:75]
	v_pk_fma_f32 v[76:77], v[76:77], v[184:185], v[144:145] op_sel_hi:[1,0,1]
	v_pk_mul_f32 v[72:73], v[140:141], v[72:73]
	v_pk_fma_f32 v[70:71], v[70:71], v[184:185], v[136:137] op_sel_hi:[1,0,1]
	v_pk_add_f32 v[68:69], v[68:69], 1.0 op_sel_hi:[1,0]
	v_rcp_f32_e32 v66, v66
	v_rcp_f32_e32 v67, v67
	v_pk_fma_f32 v[80:81], v[80:81], v[184:185], v[170:171] op_sel_hi:[1,0,1]
	v_rcp_f32_e32 v78, v78
	v_rcp_f32_e32 v79, v79
	v_pk_fma_f32 v[74:75], v[74:75], v[184:185], v[164:165] op_sel_hi:[1,0,1]
	v_exp_f32_e32 v76, v76
	v_exp_f32_e32 v77, v77
	v_pk_fma_f32 v[72:73], v[72:73], v[184:185], v[134:135] op_sel_hi:[1,0,1]
	v_exp_f32_e32 v70, v70
	v_exp_f32_e32 v71, v71
	v_rcp_f32_e32 v68, v68
	v_rcp_f32_e32 v69, v69
	v_exp_f32_e32 v80, v80
	v_exp_f32_e32 v81, v81
	v_exp_f32_e32 v74, v74
	v_exp_f32_e32 v75, v75
	v_exp_f32_e32 v72, v72
	v_exp_f32_e32 v73, v73
	v_pk_fma_f32 v[66:67], v[66:67], s[26:27], v[126:127] op_sel_hi:[1,0,0]
	v_pk_fma_f32 v[78:79], v[78:79], s[26:27], v[126:127] op_sel_hi:[1,0,0]
	v_pk_add_f32 v[76:77], v[76:77], 1.0 op_sel_hi:[1,0]
	v_pk_add_f32 v[70:71], v[70:71], 1.0 op_sel_hi:[1,0]
	v_pk_fma_f32 v[68:69], v[68:69], s[26:27], v[126:127] op_sel_hi:[1,0,0]
	v_max_f32_e32 v67, 0x4b000001, v67
	v_max_f32_e32 v66, 0x4b000001, v66
	v_pk_add_f32 v[80:81], v[80:81], 1.0 op_sel_hi:[1,0]
	v_max_f32_e32 v79, 0x4b000001, v79
	v_max_f32_e32 v78, 0x4b000001, v78
	v_pk_add_f32 v[74:75], v[74:75], 1.0 op_sel_hi:[1,0]
	v_rcp_f32_e32 v76, v76
	v_rcp_f32_e32 v77, v77
	v_pk_add_f32 v[72:73], v[72:73], 1.0 op_sel_hi:[1,0]
	v_rcp_f32_e32 v70, v70
	v_rcp_f32_e32 v71, v71
	v_perm_b32 v66, v67, v66, s58
	v_max_f32_e32 v67, 0x4b000001, v69
	v_max_f32_e32 v68, 0x4b000001, v68
	v_rcp_f32_e32 v80, v80
	v_rcp_f32_e32 v81, v81
	v_perm_b32 v84, v79, v78, s58
	v_rcp_f32_e32 v78, v74
	v_rcp_f32_e32 v79, v75
	v_rcp_f32_e32 v72, v72
	v_rcp_f32_e32 v73, v73
	v_perm_b32 v67, v67, v68, s58
	v_pk_fma_f32 v[76:77], v[76:77], s[26:27], v[126:127] op_sel_hi:[1,0,0]
	v_pk_fma_f32 v[70:71], v[70:71], s[26:27], v[126:127] op_sel_hi:[1,0,0]
	v_pk_fma_f32 v[80:81], v[80:81], s[26:27], v[126:127] op_sel_hi:[1,0,0]
	v_pk_fma_f32 v[78:79], v[78:79], s[26:27], v[126:127] op_sel_hi:[1,0,0]
	v_max_f32_e32 v77, 0x4b000001, v77
	v_max_f32_e32 v76, 0x4b000001, v76
	v_pk_fma_f32 v[72:73], v[72:73], s[26:27], v[126:127] op_sel_hi:[1,0,0]
	v_max_f32_e32 v71, 0x4b000001, v71
	v_max_f32_e32 v70, 0x4b000001, v70
	v_mad_i64_i32 v[82:83], s[2:3], v192, s57, v[142:143]
	v_max_f32_e32 v81, 0x4b000001, v81
	v_max_f32_e32 v80, 0x4b000001, v80
	v_max_f32_e32 v75, 0x4b000001, v79
	v_max_f32_e32 v78, 0x4b000001, v78
	v_perm_b32 v76, v77, v76, s58
	v_perm_b32 v70, v71, v70, s58
	v_max_f32_e32 v71, 0x4b000001, v73
	v_max_f32_e32 v72, 0x4b000001, v72
	v_lshl_or_b32 v77, v67, 16, v66
	v_lshl_add_u64 v[82:83], v[82:83], 0, s[0:1]
	v_perm_b32 v74, v81, v80, s58
	v_perm_b32 v75, v75, v78, s58
	v_perm_b32 v71, v71, v72, s58
	v_lshl_add_u64 v[82:83], v[82:83], 0, v[154:155]
	v_lshl_or_b32 v74, v74, 16, v84
	v_lshl_or_b32 v75, v76, 16, v75
	v_lshl_or_b32 v76, v71, 16, v70
	global_store_dwordx4 v[82:83], v[74:77], off
	v_pk_mul_f32 v[50:51], v[130:131], v[50:51]
	v_pk_mul_f32 v[62:63], v[174:175], v[62:63]
	v_pk_mul_f32 v[52:53], v[132:133], v[52:53]
	v_pk_fma_f32 v[50:51], v[50:51], v[182:183], v[128:129] op_sel_hi:[1,0,1]
	v_pk_fma_f32 v[62:63], v[62:63], v[182:183], v[172:173] op_sel_hi:[1,0,1]
	v_cvt_f32_i32_e32 v61, v61
	v_cvt_f32_i32_e32 v60, v60
	v_cvt_f32_i32_e32 v55, v55
	v_cvt_f32_i32_e32 v54, v54
	v_pk_fma_f32 v[52:53], v[52:53], v[182:183], v[124:125] op_sel_hi:[1,0,1]
	v_exp_f32_e32 v50, v50
	v_exp_f32_e32 v51, v51
	v_cvt_f32_i32_e32 v65, v65
	v_cvt_f32_i32_e32 v64, v64
	v_exp_f32_e32 v62, v62
	v_exp_f32_e32 v63, v63
	v_cvt_f32_i32_e32 v59, v59
	v_cvt_f32_i32_e32 v58, v58
	v_cvt_f32_i32_e32 v57, v57
	v_cvt_f32_i32_e32 v56, v56
	v_exp_f32_e32 v52, v52
	v_exp_f32_e32 v53, v53
	v_pk_mul_f32 v[60:61], v[168:169], v[60:61]
	v_pk_mul_f32 v[54:55], v[138:139], v[54:55]
	v_pk_add_f32 v[50:51], v[50:51], 1.0 op_sel_hi:[1,0]
	v_pk_mul_f32 v[64:65], v[176:177], v[64:65]
	v_pk_add_f32 v[62:63], v[62:63], 1.0 op_sel_hi:[1,0]
	v_pk_mul_f32 v[58:59], v[166:167], v[58:59]
	v_pk_fma_f32 v[60:61], v[60:61], v[182:183], v[144:145] op_sel_hi:[1,0,1]
	v_pk_mul_f32 v[56:57], v[140:141], v[56:57]
	v_pk_fma_f32 v[54:55], v[54:55], v[182:183], v[136:137] op_sel_hi:[1,0,1]
;     __device__ __forceinline__ void operator()(const f32x4 (&acc)[2][2][4][2], const Unit& u, int wr, int wc, int fr, int fq) const {
;     ...
; #pragma unroll
;         for (int ai = 0; ai < 2; ++ai)
; #pragma unroll
;             for (int m = 0; m < 4; ++m) { unsigned char* rowp = O + (size_t)(row0 + ai * HALF + m * 16) * 8704 + gbase + (col0 & 1023);
;                 const float rs = rsv[ai * 4 + m];
;                 u32x4 w; EPG_Q4(w.x, acc[ai][0][m][0], wv[0][0], rs, bv[0][0]); EPG_Q4(w.y, acc[ai][0][m][1], wv[0][1], rs, bv[0][1]);
;                 EPG_Q4(w.z, acc[ai][1][m][0], wv[1][0], rs, bv[1][0]); EPG_Q4(w.w, acc[ai][1][m][1], wv[1][1], rs, bv[1][1]);
;                 *(u32x4*)rowp = w; }
	v_pk_add_f32 v[52:53], v[52:53], 1.0 op_sel_hi:[1,0]
	v_rcp_f32_e32 v50, v50
	v_rcp_f32_e32 v51, v51
	v_pk_fma_f32 v[64:65], v[64:65], v[182:183], v[170:171] op_sel_hi:[1,0,1]
	v_rcp_f32_e32 v62, v62
	v_rcp_f32_e32 v63, v63
	v_pk_fma_f32 v[58:59], v[58:59], v[182:183], v[164:165] op_sel_hi:[1,0,1]
	v_exp_f32_e32 v60, v60
	v_exp_f32_e32 v61, v61
	v_pk_fma_f32 v[56:57], v[56:57], v[182:183], v[134:135] op_sel_hi:[1,0,1]
	v_exp_f32_e32 v54, v54
	v_exp_f32_e32 v55, v55
	v_rcp_f32_e32 v52, v52
	v_rcp_f32_e32 v53, v53
	v_exp_f32_e32 v64, v64
	v_exp_f32_e32 v65, v65
	v_exp_f32_e32 v58, v58
	v_exp_f32_e32 v59, v59
	v_exp_f32_e32 v56, v56
	v_exp_f32_e32 v57, v57
	v_pk_fma_f32 v[50:51], v[50:51], s[26:27], v[126:127] op_sel_hi:[1,0,0]
	v_pk_fma_f32 v[62:63], v[62:63], s[26:27], v[126:127] op_sel_hi:[1,0,0]
	v_pk_add_f32 v[60:61], v[60:61], 1.0 op_sel_hi:[1,0]
	v_pk_add_f32 v[54:55], v[54:55], 1.0 op_sel_hi:[1,0]
	v_pk_fma_f32 v[52:53], v[52:53], s[26:27], v[126:127] op_sel_hi:[1,0,0]
	v_max_f32_e32 v51, 0x4b000001, v51
	v_max_f32_e32 v50, 0x4b000001, v50
	v_pk_add_f32 v[64:65], v[64:65], 1.0 op_sel_hi:[1,0]
	v_max_f32_e32 v63, 0x4b000001, v63
	v_max_f32_e32 v62, 0x4b000001, v62
	v_pk_add_f32 v[58:59], v[58:59], 1.0 op_sel_hi:[1,0]
	v_rcp_f32_e32 v60, v60
	v_rcp_f32_e32 v61, v61
	v_pk_add_f32 v[56:57], v[56:57], 1.0 op_sel_hi:[1,0]
	v_rcp_f32_e32 v54, v54
	v_rcp_f32_e32 v55, v55
	v_perm_b32 v50, v51, v50, s58
	v_max_f32_e32 v51, 0x4b000001, v53
	v_max_f32_e32 v52, 0x4b000001, v52
	v_rcp_f32_e32 v64, v64
	v_rcp_f32_e32 v65, v65
	v_perm_b32 v68, v63, v62, s58
	v_rcp_f32_e32 v62, v58
	v_rcp_f32_e32 v63, v59
	v_rcp_f32_e32 v56, v56
	v_rcp_f32_e32 v57, v57
	v_perm_b32 v51, v51, v52, s58
	v_pk_fma_f32 v[60:61], v[60:61], s[26:27], v[126:127] op_sel_hi:[1,0,0]
	v_pk_fma_f32 v[54:55], v[54:55], s[26:27], v[126:127] op_sel_hi:[1,0,0]
	v_pk_fma_f32 v[64:65], v[64:65], s[26:27], v[126:127] op_sel_hi:[1,0,0]
	v_pk_fma_f32 v[62:63], v[62:63], s[26:27], v[126:127] op_sel_hi:[1,0,0]
	v_max_f32_e32 v61, 0x4b000001, v61
	v_max_f32_e32 v60, 0x4b000001, v60
	v_pk_fma_f32 v[56:57], v[56:57], s[26:27], v[126:127] op_sel_hi:[1,0,0]
	v_max_f32_e32 v55, 0x4b000001, v55
	v_max_f32_e32 v54, 0x4b000001, v54
	v_mad_i64_i32 v[66:67], s[2:3], v191, s57, v[142:143]
	v_max_f32_e32 v65, 0x4b000001, v65
	v_max_f32_e32 v64, 0x4b000001, v64
	v_max_f32_e32 v59, 0x4b000001, v63
	v_max_f32_e32 v62, 0x4b000001, v62
	v_perm_b32 v60, v61, v60, s58
	v_perm_b32 v54, v55, v54, s58
	v_max_f32_e32 v55, 0x4b000001, v57
	v_max_f32_e32 v56, 0x4b000001, v56
	v_lshl_or_b32 v61, v51, 16, v50
	v_lshl_add_u64 v[66:67], v[66:67], 0, s[0:1]
	v_perm_b32 v58, v65, v64, s58
	v_perm_b32 v59, v59, v62, s58
	v_perm_b32 v55, v55, v56, s58
	v_lshl_add_u64 v[66:67], v[66:67], 0, v[154:155]
	v_lshl_or_b32 v58, v58, 16, v68
	v_lshl_or_b32 v59, v60, 16, v59
	v_lshl_or_b32 v60, v55, 16, v54
	global_store_dwordx4 v[66:67], v[58:61], off
	v_pk_mul_f32 v[34:35], v[130:131], v[34:35]
	v_pk_mul_f32 v[46:47], v[174:175], v[46:47]
	v_pk_mul_f32 v[36:37], v[132:133], v[36:37]
	v_pk_fma_f32 v[34:35], v[34:35], v[180:181], v[128:129] op_sel_hi:[1,0,1]
	v_pk_fma_f32 v[46:47], v[46:47], v[180:181], v[172:173] op_sel_hi:[1,0,1]
	v_cvt_f32_i32_e32 v45, v45
	v_cvt_f32_i32_e32 v44, v44
	v_cvt_f32_i32_e32 v39, v39
	v_cvt_f32_i32_e32 v38, v38
	v_pk_fma_f32 v[36:37], v[36:37], v[180:181], v[124:125] op_sel_hi:[1,0,1]
	v_exp_f32_e32 v34, v34
	v_exp_f32_e32 v35, v35
	v_cvt_f32_i32_e32 v49, v49
	v_cvt_f32_i32_e32 v48, v48
	v_exp_f32_e32 v46, v46
	v_exp_f32_e32 v47, v47
	v_cvt_f32_i32_e32 v43, v43
	v_cvt_f32_i32_e32 v42, v42
	v_cvt_f32_i32_e32 v41, v41
	v_cvt_f32_i32_e32 v40, v40
	v_exp_f32_e32 v36, v36
	v_exp_f32_e32 v37, v37
	v_pk_mul_f32 v[44:45], v[168:169], v[44:45]
	v_pk_mul_f32 v[38:39], v[138:139], v[38:39]
	v_pk_add_f32 v[34:35], v[34:35], 1.0 op_sel_hi:[1,0]
	v_pk_mul_f32 v[48:49], v[176:177], v[48:49]
	v_pk_add_f32 v[46:47], v[46:47], 1.0 op_sel_hi:[1,0]
	v_pk_mul_f32 v[42:43], v[166:167], v[42:43]
	v_pk_fma_f32 v[44:45], v[44:45], v[180:181], v[144:145] op_sel_hi:[1,0,1]
	v_pk_mul_f32 v[40:41], v[140:141], v[40:41]
	v_pk_fma_f32 v[38:39], v[38:39], v[180:181], v[136:137] op_sel_hi:[1,0,1]
	v_pk_add_f32 v[36:37], v[36:37], 1.0 op_sel_hi:[1,0]
	v_rcp_f32_e32 v34, v34
	v_rcp_f32_e32 v35, v35
	v_pk_fma_f32 v[48:49], v[48:49], v[180:181], v[170:171] op_sel_hi:[1,0,1]
	v_rcp_f32_e32 v46, v46
	v_rcp_f32_e32 v47, v47
	v_pk_fma_f32 v[42:43], v[42:43], v[180:181], v[164:165] op_sel_hi:[1,0,1]
	v_exp_f32_e32 v44, v44
	v_exp_f32_e32 v45, v45
	v_pk_fma_f32 v[40:41], v[40:41], v[180:181], v[134:135] op_sel_hi:[1,0,1]
	v_exp_f32_e32 v38, v38
	v_exp_f32_e32 v39, v39
	v_rcp_f32_e32 v36, v36
	v_rcp_f32_e32 v37, v37
	v_exp_f32_e32 v48, v48
	v_exp_f32_e32 v49, v49
	v_exp_f32_e32 v42, v42
	v_exp_f32_e32 v43, v43
	v_exp_f32_e32 v40, v40
	v_exp_f32_e32 v41, v41
	v_pk_fma_f32 v[34:35], v[34:35], s[26:27], v[126:127] op_sel_hi:[1,0,0]
	v_pk_fma_f32 v[46:47], v[46:47], s[26:27], v[126:127] op_sel_hi:[1,0,0]
	v_pk_add_f32 v[44:45], v[44:45], 1.0 op_sel_hi:[1,0]
	v_pk_add_f32 v[38:39], v[38:39], 1.0 op_sel_hi:[1,0]
	v_pk_fma_f32 v[36:37], v[36:37], s[26:27], v[126:127] op_sel_hi:[1,0,0]
	v_max_f32_e32 v35, 0x4b000001, v35
	v_max_f32_e32 v34, 0x4b000001, v34
	v_pk_add_f32 v[48:49], v[48:49], 1.0 op_sel_hi:[1,0]
	v_max_f32_e32 v47, 0x4b000001, v47
	v_max_f32_e32 v46, 0x4b000001, v46
	v_pk_add_f32 v[42:43], v[42:43], 1.0 op_sel_hi:[1,0]
	v_rcp_f32_e32 v44, v44
	v_rcp_f32_e32 v45, v45
	v_pk_add_f32 v[40:41], v[40:41], 1.0 op_sel_hi:[1,0]
	v_rcp_f32_e32 v38, v38
	v_rcp_f32_e32 v39, v39
	v_perm_b32 v34, v35, v34, s58
	v_max_f32_e32 v35, 0x4b000001, v37
;     __device__ __forceinline__ void operator()(const f32x4 (&acc)[2][2][4][2], const Unit& u, int wr, int wc, int fr, int fq) const {
;     ...
; #pragma unroll
;         for (int ai = 0; ai < 2; ++ai)
; #pragma unroll
;             for (int m = 0; m < 4; ++m) { unsigned char* rowp = O + (size_t)(row0 + ai * HALF + m * 16) * 8704 + gbase + (col0 & 1023);
;                 const float rs = rsv[ai * 4 + m];
;                 u32x4 w; EPG_Q4(w.x, acc[ai][0][m][0], wv[0][0], rs, bv[0][0]); EPG_Q4(w.y, acc[ai][0][m][1], wv[0][1], rs, bv[0][1]);
;                 EPG_Q4(w.z, acc[ai][1][m][0], wv[1][0], rs, bv[1][0]); EPG_Q4(w.w, acc[ai][1][m][1], wv[1][1], rs, bv[1][1]);
;                 *(u32x4*)rowp = w; }
	v_max_f32_e32 v36, 0x4b000001, v36
	v_rcp_f32_e32 v48, v48
	v_rcp_f32_e32 v49, v49
	v_perm_b32 v52, v47, v46, s58
	v_rcp_f32_e32 v46, v42
	v_rcp_f32_e32 v47, v43
	v_rcp_f32_e32 v40, v40
	v_rcp_f32_e32 v41, v41
	v_perm_b32 v35, v35, v36, s58
	v_pk_fma_f32 v[44:45], v[44:45], s[26:27], v[126:127] op_sel_hi:[1,0,0]
	v_pk_fma_f32 v[38:39], v[38:39], s[26:27], v[126:127] op_sel_hi:[1,0,0]
	v_pk_fma_f32 v[48:49], v[48:49], s[26:27], v[126:127] op_sel_hi:[1,0,0]
	v_pk_fma_f32 v[46:47], v[46:47], s[26:27], v[126:127] op_sel_hi:[1,0,0]
	v_max_f32_e32 v45, 0x4b000001, v45
	v_max_f32_e32 v44, 0x4b000001, v44
	v_pk_fma_f32 v[40:41], v[40:41], s[26:27], v[126:127] op_sel_hi:[1,0,0]
	v_max_f32_e32 v39, 0x4b000001, v39
	v_max_f32_e32 v38, 0x4b000001, v38
	v_mad_i64_i32 v[50:51], s[2:3], v190, s57, v[142:143]
	v_max_f32_e32 v49, 0x4b000001, v49
	v_max_f32_e32 v48, 0x4b000001, v48
	v_max_f32_e32 v43, 0x4b000001, v47
	v_max_f32_e32 v46, 0x4b000001, v46
	v_perm_b32 v44, v45, v44, s58
	v_perm_b32 v38, v39, v38, s58
	v_max_f32_e32 v39, 0x4b000001, v41
	v_max_f32_e32 v40, 0x4b000001, v40
	v_lshl_or_b32 v45, v35, 16, v34
	v_lshl_add_u64 v[50:51], v[50:51], 0, s[0:1]
	v_perm_b32 v42, v49, v48, s58
	v_perm_b32 v43, v43, v46, s58
	v_perm_b32 v39, v39, v40, s58
	v_lshl_add_u64 v[50:51], v[50:51], 0, v[154:155]
	v_lshl_or_b32 v42, v42, 16, v52
	v_lshl_or_b32 v43, v44, 16, v43
	v_lshl_or_b32 v44, v39, 16, v38
	global_store_dwordx4 v[50:51], v[42:45], off
	v_pk_mul_f32 v[18:19], v[130:131], v[18:19]
	v_pk_mul_f32 v[30:31], v[174:175], v[30:31]
	v_pk_mul_f32 v[20:21], v[132:133], v[20:21]
	v_pk_fma_f32 v[18:19], v[18:19], v[178:179], v[128:129] op_sel_hi:[1,0,1]
	v_pk_fma_f32 v[30:31], v[30:31], v[178:179], v[172:173] op_sel_hi:[1,0,1]
	v_cvt_f32_i32_e32 v29, v29
	v_cvt_f32_i32_e32 v28, v28
	v_cvt_f32_i32_e32 v23, v23
	v_cvt_f32_i32_e32 v22, v22
	v_pk_fma_f32 v[20:21], v[20:21], v[178:179], v[124:125] op_sel_hi:[1,0,1]
	v_exp_f32_e32 v18, v18
	v_exp_f32_e32 v19, v19
	v_cvt_f32_i32_e32 v33, v33
	v_cvt_f32_i32_e32 v32, v32
	v_exp_f32_e32 v30, v30
	v_exp_f32_e32 v31, v31
	v_cvt_f32_i32_e32 v27, v27
	v_cvt_f32_i32_e32 v26, v26
	v_cvt_f32_i32_e32 v25, v25
	v_cvt_f32_i32_e32 v24, v24
	v_exp_f32_e32 v20, v20
	v_exp_f32_e32 v21, v21
	v_pk_mul_f32 v[28:29], v[168:169], v[28:29]
	v_pk_mul_f32 v[22:23], v[138:139], v[22:23]
	v_pk_add_f32 v[18:19], v[18:19], 1.0 op_sel_hi:[1,0]
	v_pk_mul_f32 v[32:33], v[176:177], v[32:33]
	v_pk_add_f32 v[30:31], v[30:31], 1.0 op_sel_hi:[1,0]
	v_pk_mul_f32 v[26:27], v[166:167], v[26:27]
	v_pk_fma_f32 v[28:29], v[28:29], v[178:179], v[144:145] op_sel_hi:[1,0,1]
	v_pk_mul_f32 v[24:25], v[140:141], v[24:25]
	v_pk_fma_f32 v[22:23], v[22:23], v[178:179], v[136:137] op_sel_hi:[1,0,1]
	v_pk_add_f32 v[20:21], v[20:21], 1.0 op_sel_hi:[1,0]
	v_rcp_f32_e32 v18, v18
	v_rcp_f32_e32 v19, v19
	v_pk_fma_f32 v[32:33], v[32:33], v[178:179], v[170:171] op_sel_hi:[1,0,1]
	v_rcp_f32_e32 v30, v30
	v_rcp_f32_e32 v31, v31
	v_pk_fma_f32 v[26:27], v[26:27], v[178:179], v[164:165] op_sel_hi:[1,0,1]
	v_exp_f32_e32 v28, v28
	v_exp_f32_e32 v29, v29
	v_pk_fma_f32 v[24:25], v[24:25], v[178:179], v[134:135] op_sel_hi:[1,0,1]
	v_exp_f32_e32 v22, v22
	v_exp_f32_e32 v23, v23
	v_rcp_f32_e32 v20, v20
	v_rcp_f32_e32 v21, v21
	v_exp_f32_e32 v32, v32
	v_exp_f32_e32 v33, v33
	v_exp_f32_e32 v26, v26
	v_exp_f32_e32 v27, v27
	v_exp_f32_e32 v24, v24
	v_exp_f32_e32 v25, v25
	v_pk_fma_f32 v[18:19], v[18:19], s[26:27], v[126:127] op_sel_hi:[1,0,0]
	v_pk_fma_f32 v[30:31], v[30:31], s[26:27], v[126:127] op_sel_hi:[1,0,0]
	v_pk_add_f32 v[28:29], v[28:29], 1.0 op_sel_hi:[1,0]
	v_pk_add_f32 v[22:23], v[22:23], 1.0 op_sel_hi:[1,0]
	v_pk_fma_f32 v[20:21], v[20:21], s[26:27], v[126:127] op_sel_hi:[1,0,0]
	v_max_f32_e32 v19, 0x4b000001, v19
	v_max_f32_e32 v18, 0x4b000001, v18
	v_pk_add_f32 v[32:33], v[32:33], 1.0 op_sel_hi:[1,0]
	v_max_f32_e32 v31, 0x4b000001, v31
	v_max_f32_e32 v30, 0x4b000001, v30
	v_pk_add_f32 v[26:27], v[26:27], 1.0 op_sel_hi:[1,0]
	v_rcp_f32_e32 v28, v28
	v_rcp_f32_e32 v29, v29
	v_pk_add_f32 v[24:25], v[24:25], 1.0 op_sel_hi:[1,0]
	v_rcp_f32_e32 v22, v22
	v_rcp_f32_e32 v23, v23
	v_perm_b32 v18, v19, v18, s58
	v_max_f32_e32 v19, 0x4b000001, v21
	v_max_f32_e32 v20, 0x4b000001, v20
	v_rcp_f32_e32 v32, v32
	v_rcp_f32_e32 v33, v33
	v_perm_b32 v36, v31, v30, s58
	v_rcp_f32_e32 v30, v26
	v_rcp_f32_e32 v31, v27
	v_rcp_f32_e32 v24, v24
	v_rcp_f32_e32 v25, v25
	v_perm_b32 v19, v19, v20, s58
	v_pk_fma_f32 v[28:29], v[28:29], s[26:27], v[126:127] op_sel_hi:[1,0,0]
	v_pk_fma_f32 v[22:23], v[22:23], s[26:27], v[126:127] op_sel_hi:[1,0,0]
	v_pk_fma_f32 v[32:33], v[32:33], s[26:27], v[126:127] op_sel_hi:[1,0,0]
	v_pk_fma_f32 v[30:31], v[30:31], s[26:27], v[126:127] op_sel_hi:[1,0,0]
	v_max_f32_e32 v29, 0x4b000001, v29
	v_max_f32_e32 v28, 0x4b000001, v28
	v_pk_fma_f32 v[24:25], v[24:25], s[26:27], v[126:127] op_sel_hi:[1,0,0]
	v_max_f32_e32 v23, 0x4b000001, v23
	v_max_f32_e32 v22, 0x4b000001, v22
	v_mad_i64_i32 v[34:35], s[2:3], v189, s57, v[142:143]
;     __device__ __forceinline__ void operator()(const f32x4 (&acc)[2][2][4][2], const Unit& u, int wr, int wc, int fr, int fq) const {
;     ...
; #pragma unroll
;         for (int ai = 0; ai < 2; ++ai)
; #pragma unroll
;             for (int m = 0; m < 4; ++m) { unsigned char* rowp = O + (size_t)(row0 + ai * HALF + m * 16) * 8704 + gbase + (col0 & 1023);
;                 const float rs = rsv[ai * 4 + m];
;                 u32x4 w; EPG_Q4(w.x, acc[ai][0][m][0], wv[0][0], rs, bv[0][0]); EPG_Q4(w.y, acc[ai][0][m][1], wv[0][1], rs, bv[0][1]);
;                 EPG_Q4(w.z, acc[ai][1][m][0], wv[1][0], rs, bv[1][0]); EPG_Q4(w.w, acc[ai][1][m][1], wv[1][1], rs, bv[1][1]);
;                 *(u32x4*)rowp = w; }
	v_max_f32_e32 v33, 0x4b000001, v33
	v_max_f32_e32 v32, 0x4b000001, v32
	v_max_f32_e32 v27, 0x4b000001, v31
	v_max_f32_e32 v30, 0x4b000001, v30
	v_perm_b32 v28, v29, v28, s58
	v_perm_b32 v22, v23, v22, s58
	v_max_f32_e32 v23, 0x4b000001, v25
	v_max_f32_e32 v24, 0x4b000001, v24
	v_lshl_or_b32 v29, v19, 16, v18
	v_lshl_add_u64 v[34:35], v[34:35], 0, s[0:1]
	v_perm_b32 v26, v33, v32, s58
	v_perm_b32 v27, v27, v30, s58
	v_perm_b32 v23, v23, v24, s58
	v_lshl_add_u64 v[34:35], v[34:35], 0, v[154:155]
	v_lshl_or_b32 v26, v26, 16, v36
	v_lshl_or_b32 v27, v28, 16, v27
	v_lshl_or_b32 v28, v23, 16, v22
	global_store_dwordx4 v[34:35], v[26:29], off
	v_pk_mul_f32 v[14:15], v[174:175], v[14:15]
	v_pk_fma_f32 v[14:15], v[14:15], v[122:123], v[172:173] op_sel_hi:[1,0,1]
	v_cvt_f32_i32_e32 v7, v7
	v_cvt_f32_i32_e32 v6, v6
	v_cvt_f32_i32_e32 v3, v3
	v_cvt_f32_i32_e32 v2, v2
	v_cvt_f32_i32_e32 v17, v17
	v_cvt_f32_i32_e32 v16, v16
	v_exp_f32_e32 v14, v14
	v_exp_f32_e32 v15, v15
	v_cvt_f32_i32_e32 v11, v11
	v_cvt_f32_i32_e32 v13, v13
	v_cvt_f32_i32_e32 v12, v12
	v_cvt_f32_i32_e32 v10, v10
	v_cvt_f32_i32_e32 v9, v9
	v_cvt_f32_i32_e32 v8, v8
	v_cvt_f32_i32_e32 v5, v5
	v_cvt_f32_i32_e32 v4, v4
	v_pk_mul_f32 v[6:7], v[138:139], v[6:7]
	v_pk_mul_f32 v[2:3], v[130:131], v[2:3]
	v_pk_mul_f32 v[16:17], v[176:177], v[16:17]
	v_pk_add_f32 v[14:15], v[14:15], 1.0 op_sel_hi:[1,0]
	v_pk_mul_f32 v[12:13], v[168:169], v[12:13]
	v_pk_mul_f32 v[10:11], v[166:167], v[10:11]
	v_pk_mul_f32 v[8:9], v[140:141], v[8:9]
	v_pk_fma_f32 v[6:7], v[6:7], v[122:123], v[136:137] op_sel_hi:[1,0,1]
	v_pk_mul_f32 v[4:5], v[132:133], v[4:5]
	v_pk_fma_f32 v[2:3], v[2:3], v[122:123], v[128:129] op_sel_hi:[1,0,1]
	v_pk_fma_f32 v[16:17], v[16:17], v[122:123], v[170:171] op_sel_hi:[1,0,1]
	v_rcp_f32_e32 v14, v14
	v_rcp_f32_e32 v15, v15
	v_pk_fma_f32 v[12:13], v[12:13], v[122:123], v[144:145] op_sel_hi:[1,0,1]
	v_pk_fma_f32 v[10:11], v[10:11], v[122:123], v[164:165] op_sel_hi:[1,0,1]
	v_pk_fma_f32 v[8:9], v[8:9], v[122:123], v[134:135] op_sel_hi:[1,0,1]
	v_exp_f32_e32 v6, v6
	v_exp_f32_e32 v7, v7
	v_pk_fma_f32 v[4:5], v[4:5], v[122:123], v[124:125] op_sel_hi:[1,0,1]
	v_exp_f32_e32 v2, v2
	v_exp_f32_e32 v3, v3
	v_exp_f32_e32 v16, v16
	v_exp_f32_e32 v17, v17
	v_exp_f32_e32 v10, v10
	v_exp_f32_e32 v12, v12
	v_exp_f32_e32 v13, v13
	v_exp_f32_e32 v11, v11
	v_exp_f32_e32 v8, v8
	v_exp_f32_e32 v9, v9
	v_exp_f32_e32 v4, v4
	v_exp_f32_e32 v5, v5
	v_pk_fma_f32 v[14:15], v[14:15], s[26:27], v[126:127] op_sel_hi:[1,0,0]
	v_pk_add_f32 v[6:7], v[6:7], 1.0 op_sel_hi:[1,0]
	v_pk_add_f32 v[2:3], v[2:3], 1.0 op_sel_hi:[1,0]
	v_pk_add_f32 v[16:17], v[16:17], 1.0 op_sel_hi:[1,0]
	v_max_f32_e32 v15, 0x4b000001, v15
	v_max_f32_e32 v14, 0x4b000001, v14
	v_pk_add_f32 v[12:13], v[12:13], 1.0 op_sel_hi:[1,0]
	v_pk_add_f32 v[10:11], v[10:11], 1.0 op_sel_hi:[1,0]
	v_pk_add_f32 v[8:9], v[8:9], 1.0 op_sel_hi:[1,0]
	v_rcp_f32_e32 v6, v6
	v_rcp_f32_e32 v7, v7
	v_pk_add_f32 v[4:5], v[4:5], 1.0 op_sel_hi:[1,0]
	v_rcp_f32_e32 v2, v2
	v_rcp_f32_e32 v3, v3
	v_rcp_f32_e32 v16, v16
	v_rcp_f32_e32 v17, v17
	v_perm_b32 v20, v15, v14, s58
	v_rcp_f32_e32 v14, v10
	v_rcp_f32_e32 v12, v12
	v_rcp_f32_e32 v13, v13
	v_rcp_f32_e32 v15, v11
	v_rcp_f32_e32 v8, v8
	v_rcp_f32_e32 v9, v9
	v_rcp_f32_e32 v4, v4
	v_rcp_f32_e32 v5, v5
	v_pk_fma_f32 v[6:7], v[6:7], s[26:27], v[126:127] op_sel_hi:[1,0,0]
	v_pk_fma_f32 v[2:3], v[2:3], s[26:27], v[126:127] op_sel_hi:[1,0,0]
	v_pk_fma_f32 v[16:17], v[16:17], s[26:27], v[126:127] op_sel_hi:[1,0,0]
	v_pk_fma_f32 v[12:13], v[12:13], s[26:27], v[126:127] op_sel_hi:[1,0,0]
	v_pk_fma_f32 v[14:15], v[14:15], s[26:27], v[126:127] op_sel_hi:[1,0,0]
	v_pk_fma_f32 v[8:9], v[8:9], s[26:27], v[126:127] op_sel_hi:[1,0,0]
	v_max_f32_e32 v7, 0x4b000001, v7
	v_max_f32_e32 v6, 0x4b000001, v6
	v_pk_fma_f32 v[4:5], v[4:5], s[26:27], v[126:127] op_sel_hi:[1,0,0]
	v_max_f32_e32 v3, 0x4b000001, v3
	v_max_f32_e32 v2, 0x4b000001, v2
	v_mad_i64_i32 v[18:19], s[2:3], v123, s57, v[142:143]
	v_max_f32_e32 v17, 0x4b000001, v17
	v_max_f32_e32 v16, 0x4b000001, v16
	v_max_f32_e32 v11, 0x4b000001, v15
	v_max_f32_e32 v14, 0x4b000001, v14
	v_max_f32_e32 v13, 0x4b000001, v13
	v_max_f32_e32 v12, 0x4b000001, v12
	v_perm_b32 v6, v7, v6, s58
	v_max_f32_e32 v7, 0x4b000001, v9
	v_max_f32_e32 v8, 0x4b000001, v8
	v_perm_b32 v2, v3, v2, s58
	v_max_f32_e32 v3, 0x4b000001, v5
	v_max_f32_e32 v4, 0x4b000001, v4
	v_lshl_add_u64 v[18:19], v[18:19], 0, s[0:1]
	v_perm_b32 v10, v17, v16, s58
	v_perm_b32 v11, v11, v14, s58
	v_perm_b32 v12, v13, v12, s58
	v_perm_b32 v7, v7, v8, s58
	v_perm_b32 v3, v3, v4, s58
	v_lshl_add_u64 v[18:19], v[18:19], 0, v[154:155]
	v_lshl_or_b32 v10, v10, 16, v20
	v_lshl_or_b32 v11, v12, 16, v11
	v_lshl_or_b32 v12, v7, 16, v6
	v_lshl_or_b32 v13, v3, 16, v2
	global_store_dwordx4 v[18:19], v[10:13], off
	s_andn2_b64 vcc, exec, s[4:5]
	s_mov_b64 s[0:1], -1
	s_cbranch_vccnz .LBB0_1184
	s_andn2_b64 vcc, exec, s[6:7]
	s_cbranch_vccnz .LBB0_1183
	s_barrier
	s_branch .LBB0_1183

;     __device__ __forceinline__ void operator()(const f32x4 (&acc)[2][2][4][2], const Unit& u, int wr, int wc, int fr, int fq) const {
;     ...
;         const int row0 = u.pm * BM + wr * 64 + fr, col0 = u.pn * BM + wc * 64 + 16 * fq;
;         const int gn = u.pn >> 2, gbase = (gn < 3) ? 3072 + 1024 * gn : 0;
;         f32x4 bv[2][2];
; #pragma unroll
;         for (int bj = 0; bj < 2; ++bj)
; #pragma unroll
;             for (int n = 0; n < 2; ++n) bv[bj][n] = *(const f32x4*)(bias + col0 + 8 * bj + 4 * n) * -1.44269504f;
;         f32x4 wv[2][2];
; #pragma unroll
;         for (int bj = 0; bj < 2; ++bj)
; #pragma unroll
;             for (int n = 0; n < 2; ++n) wv[bj][n] = *(const f32x4*)(SW + col0 + 8 * bj + 4 * n) * -1.44269504f;
;         float rsv[8];
; #pragma unroll
;         for (int i = 0; i < 8; ++i) rsv[i] = SH[row0 + (i >> 2) * HALF + (i & 3) * 16];
;     ...
; #pragma unroll
;         for (int ai = 0; ai < 2; ++ai)
; #pragma unroll
;             for (int m = 0; m < 4; ++m) { unsigned char* rowp = O + (size_t)(row0 + ai * HALF + m * 16) * 8704 + gbase + (col0 & 1023);
;                 const float rs = rsv[ai * 4 + m];
;                 u32x4 w; EPG_Q4(w.x, acc[ai][0][m][0], wv[0][0], rs, bv[0][0]); EPG_Q4(w.y, acc[ai][0][m][1], wv[0][1], rs, bv[0][1]);
;                 EPG_Q4(w.z, acc[ai][1][m][0], wv[1][0], rs, bv[1][0]); EPG_Q4(w.w, acc[ai][1][m][1], wv[1][1], rs, bv[1][1]);
;                 *(u32x4*)rowp = w; }
.LBB0_2555:
	s_lshl_b32 s0, s59, 8
	v_mov_b32_e32 v154, v1
	v_mov_b32_e32 v130, v179
	s_or_b32 s0, s0, s53
	v_cvt_f32_i32_e32 v212, v122
	v_lshl_add_u32 v144, v130, 4, s0
	s_lshl_b32 s0, s38, 8
	v_ashrrev_i32_e32 v145, 31, v144
	s_add_i32 s0, s0, s50
	v_lshlrev_b64 v[142:143], 2, v[144:145]
	v_add_u32_e32 v164, s0, v154
	v_lshl_add_u64 v[160:161], s[14:15], 0, v[142:143]
	v_ashrrev_i32_e32 v165, 31, v164
	global_load_dwordx4 v[130:133], v[160:161], off
	global_load_dwordx4 v[134:137], v[160:161], off offset:16
	global_load_dwordx4 v[138:141], v[160:161], off offset:32
	s_nop 0
	global_load_dwordx4 v[160:163], v[160:161], off offset:48
	v_lshl_add_u64 v[142:143], s[16:17], 0, v[142:143]
	v_lshl_add_u64 v[170:171], v[164:165], 2, s[12:13]
	global_load_dwordx4 v[166:169], v[142:143], off
	global_load_dwordx4 v[194:197], v[142:143], off offset:16
	global_load_dwordx4 v[198:201], v[142:143], off offset:32
	global_load_dwordx4 v[202:205], v[142:143], off offset:48
	global_load_dword v206, v[170:171], off
	global_load_dword v188, v[170:171], off offset:64
	global_load_dword v186, v[170:171], off offset:128
	global_load_dword v184, v[170:171], off offset:192
	global_load_dword v182, v[170:171], off offset:512
	global_load_dword v180, v[170:171], off offset:576
	global_load_dword v178, v[170:171], off offset:640
	global_load_dword v122, v[170:171], off offset:704
	s_ashr_i32 s0, s59, 2
	s_lshl_b32 s1, s0, 10
	v_mov_b64_e32 v[142:143], s[10:11]
	s_add_i32 s2, s1, 0xc00
	v_cvt_f32_i32_e32 v209, v127
	v_cvt_f32_i32_e32 v208, v126
	v_cvt_f32_i32_e32 v215, v125
	v_cvt_f32_i32_e32 v214, v124
	s_cmp_lt_i32 s0, 3
	v_mad_i64_i32 v[124:125], s[0:1], v164, s57, v[142:143]
	s_cselect_b32 s0, s2, 0
	v_cvt_f32_i32_e32 v211, v129
	v_cvt_f32_i32_e32 v210, v128
	s_ashr_i32 s1, s0, 31
	v_cvt_f32_i32_e32 v115, v115
	v_cvt_f32_i32_e32 v114, v114
	v_cvt_f32_i32_e32 v99, v99
	v_cvt_f32_i32_e32 v98, v98
	v_cvt_f32_i32_e32 v83, v83
	v_cvt_f32_i32_e32 v82, v82
	v_cvt_f32_i32_e32 v67, v67
	v_cvt_f32_i32_e32 v66, v66
	v_cvt_f32_i32_e32 v51, v51
	v_cvt_f32_i32_e32 v50, v50
	v_cvt_f32_i32_e32 v35, v35
	v_cvt_f32_i32_e32 v34, v34
	v_cvt_f32_i32_e32 v19, v19
	v_cvt_f32_i32_e32 v18, v18
	v_and_b32_e32 v154, 0x3f0, v144
	v_lshl_add_u64 v[124:125], v[124:125], 0, s[0:1]
	v_cvt_f32_i32_e32 v117, v117
	v_cvt_f32_i32_e32 v116, v116
	v_cvt_f32_i32_e32 v111, v111
	v_cvt_f32_i32_e32 v110, v110
	v_cvt_f32_i32_e32 v101, v101
	v_cvt_f32_i32_e32 v100, v100
	v_cvt_f32_i32_e32 v95, v95
	v_cvt_f32_i32_e32 v94, v94
	v_cvt_f32_i32_e32 v85, v85
	v_cvt_f32_i32_e32 v84, v84
	v_cvt_f32_i32_e32 v79, v79
	v_cvt_f32_i32_e32 v78, v78
	v_cvt_f32_i32_e32 v69, v69
	v_cvt_f32_i32_e32 v68, v68
	v_cvt_f32_i32_e32 v63, v63
	v_cvt_f32_i32_e32 v62, v62
	v_cvt_f32_i32_e32 v53, v53
	v_cvt_f32_i32_e32 v52, v52
	v_cvt_f32_i32_e32 v47, v47
	v_cvt_f32_i32_e32 v46, v46
	v_cvt_f32_i32_e32 v37, v37
	v_cvt_f32_i32_e32 v36, v36
	v_cvt_f32_i32_e32 v31, v31
	v_cvt_f32_i32_e32 v30, v30
	v_cvt_f32_i32_e32 v21, v21
	v_cvt_f32_i32_e32 v20, v20
	v_cvt_f32_i32_e32 v15, v15
	v_cvt_f32_i32_e32 v14, v14
	v_add_u32_e32 v207, 32, v164
	v_lshl_add_u64 v[216:217], v[124:125], 0, v[154:155]
	v_add_u32_e32 v189, 0xa0, v164
	v_cvt_f32_i32_e32 v213, v123
	v_add_u32_e32 v123, 0xb0, v164
	v_cvt_f32_i32_e32 v119, v119
	v_cvt_f32_i32_e32 v118, v118
	v_cvt_f32_i32_e32 v109, v109
	v_cvt_f32_i32_e32 v108, v108
	v_cvt_f32_i32_e32 v103, v103
	v_cvt_f32_i32_e32 v102, v102
	v_cvt_f32_i32_e32 v93, v93
	s_waitcnt vmcnt(0)
	v_pk_mul_f32 v[172:173], v[130:131], s[22:23] op_sel_hi:[1,0]
	v_pk_mul_f32 v[170:171], v[132:133], s[22:23] op_sel_hi:[1,0]
	v_pk_mul_f32 v[174:175], v[166:167], s[22:23] op_sel_hi:[1,0]
	v_pk_mul_f32 v[124:125], v[162:163], s[22:23] op_sel_hi:[1,0]
	v_pk_mul_f32 v[162:163], v[174:175], v[208:209]
	v_pk_mul_f32 v[176:177], v[168:169], s[22:23] op_sel_hi:[1,0]
	v_pk_mul_f32 v[130:131], v[202:203], s[22:23] op_sel_hi:[1,0]
	v_pk_fma_f32 v[162:163], v[162:163], v[206:207], v[172:173] op_sel_hi:[1,0,1]
	v_pk_mul_f32 v[128:129], v[160:161], s[22:23] op_sel_hi:[1,0]
	v_pk_mul_f32 v[132:133], v[204:205], s[22:23] op_sel_hi:[1,0]
	v_pk_mul_f32 v[160:161], v[176:177], v[210:211]
	v_exp_f32_e32 v162, v162
	v_exp_f32_e32 v163, v163
	v_pk_mul_f32 v[114:115], v[130:131], v[114:115]
	v_pk_fma_f32 v[160:161], v[160:161], v[206:207], v[170:171] op_sel_hi:[1,0,1]
	v_pk_mul_f32 v[116:117], v[132:133], v[116:117]
	v_pk_fma_f32 v[114:115], v[114:115], v[206:207], v[128:129] op_sel_hi:[1,0,1]
	v_exp_f32_e32 v160, v160
	v_exp_f32_e32 v161, v161
	v_pk_fma_f32 v[116:117], v[116:117], v[206:207], v[124:125] op_sel_hi:[1,0,1]
	v_exp_f32_e32 v114, v114
	v_exp_f32_e32 v115, v115
	v_cvt_f32_i32_e32 v121, v121
	v_cvt_f32_i32_e32 v120, v120
	v_exp_f32_e32 v116, v116
	v_exp_f32_e32 v117, v117
	v_pk_mul_f32 v[166:167], v[194:195], s[22:23] op_sel_hi:[1,0]
	v_pk_add_f32 v[162:163], v[162:163], 1.0 op_sel_hi:[1,0]
	v_add_u32_e32 v193, 16, v164
	v_add_u32_e32 v192, 48, v164
	v_add_u32_e32 v191, 0x80, v164
	v_add_u32_e32 v190, 0x90, v164
	v_pk_mul_f32 v[144:145], v[136:137], s[22:23] op_sel_hi:[1,0]
	v_pk_mul_f32 v[164:165], v[134:135], s[22:23] op_sel_hi:[1,0]
	v_pk_mul_f32 v[136:137], v[138:139], s[22:23] op_sel_hi:[1,0]
	v_pk_mul_f32 v[168:169], v[196:197], s[22:23] op_sel_hi:[1,0]
	v_pk_mul_f32 v[138:139], v[198:199], s[22:23] op_sel_hi:[1,0]
	v_pk_mul_f32 v[196:197], v[166:167], v[212:213]
	v_rcp_f32_e32 v162, v162
	v_rcp_f32_e32 v163, v163
	v_pk_mul_f32 v[134:135], v[140:141], s[22:23] op_sel_hi:[1,0]
	v_pk_mul_f32 v[140:141], v[200:201], s[22:23] op_sel_hi:[1,0]
	v_pk_mul_f32 v[194:195], v[168:169], v[214:215]
	v_pk_fma_f32 v[196:197], v[196:197], v[206:207], v[164:165] op_sel_hi:[1,0,1]
;     __device__ __forceinline__ void operator()(const f32x4 (&acc)[2][2][4][2], const Unit& u, int wr, int wc, int fr, int fq) const {
;     ...
; #pragma unroll
;         for (int ai = 0; ai < 2; ++ai)
; #pragma unroll
;             for (int m = 0; m < 4; ++m) { unsigned char* rowp = O + (size_t)(row0 + ai * HALF + m * 16) * 8704 + gbase + (col0 & 1023);
;                 const float rs = rsv[ai * 4 + m];
;                 u32x4 w; EPG_Q4(w.x, acc[ai][0][m][0], wv[0][0], rs, bv[0][0]); EPG_Q4(w.y, acc[ai][0][m][1], wv[0][1], rs, bv[0][1]);
;                 EPG_Q4(w.z, acc[ai][1][m][0], wv[1][0], rs, bv[1][0]); EPG_Q4(w.w, acc[ai][1][m][1], wv[1][1], rs, bv[1][1]);
;                 *(u32x4*)rowp = w; }
	v_pk_add_f32 v[160:161], v[160:161], 1.0 op_sel_hi:[1,0]
	v_pk_mul_f32 v[118:119], v[138:139], v[118:119]
	v_pk_add_f32 v[114:115], v[114:115], 1.0 op_sel_hi:[1,0]
	v_pk_fma_f32 v[194:195], v[194:195], v[206:207], v[144:145] op_sel_hi:[1,0,1]
	v_exp_f32_e32 v196, v196
	v_rcp_f32_e32 v160, v160
	v_rcp_f32_e32 v161, v161
	v_exp_f32_e32 v197, v197
	v_pk_mul_f32 v[120:121], v[140:141], v[120:121]
	v_pk_fma_f32 v[118:119], v[118:119], v[206:207], v[136:137] op_sel_hi:[1,0,1]
	v_pk_add_f32 v[116:117], v[116:117], 1.0 op_sel_hi:[1,0]
	v_rcp_f32_e32 v114, v114
	v_rcp_f32_e32 v115, v115
	v_mov_b64_e32 v[126:127], s[24:25]
	v_exp_f32_e32 v194, v194
	v_exp_f32_e32 v195, v195
	v_pk_fma_f32 v[120:121], v[120:121], v[206:207], v[134:135] op_sel_hi:[1,0,1]
	v_exp_f32_e32 v118, v118
	v_exp_f32_e32 v119, v119
	v_rcp_f32_e32 v116, v116
	v_rcp_f32_e32 v117, v117
	v_pk_fma_f32 v[162:163], v[162:163], s[26:27], v[126:127] op_sel_hi:[1,0,0]
	v_exp_f32_e32 v120, v120
	v_exp_f32_e32 v121, v121
	v_max_f32_e32 v163, 0x4b000001, v163
	v_max_f32_e32 v162, 0x4b000001, v162
	v_pk_fma_f32 v[160:161], v[160:161], s[26:27], v[126:127] op_sel_hi:[1,0,0]
	v_perm_b32 v198, v163, v162, s58
	v_pk_add_f32 v[162:163], v[196:197], 1.0 op_sel_hi:[1,0]
	v_pk_fma_f32 v[114:115], v[114:115], s[26:27], v[126:127] op_sel_hi:[1,0,0]
	v_max_f32_e32 v199, 0x4b000001, v161
	v_max_f32_e32 v200, 0x4b000001, v160
	v_pk_add_f32 v[160:161], v[194:195], 1.0 op_sel_hi:[1,0]
	v_rcp_f32_e32 v162, v162
	v_rcp_f32_e32 v163, v163
	v_pk_add_f32 v[118:119], v[118:119], 1.0 op_sel_hi:[1,0]
	v_pk_fma_f32 v[116:117], v[116:117], s[26:27], v[126:127] op_sel_hi:[1,0,0]
	v_max_f32_e32 v115, 0x4b000001, v115
	v_max_f32_e32 v114, 0x4b000001, v114
	v_rcp_f32_e32 v194, v160
	v_rcp_f32_e32 v195, v161
	v_pk_add_f32 v[120:121], v[120:121], 1.0 op_sel_hi:[1,0]
	v_rcp_f32_e32 v118, v118
	v_rcp_f32_e32 v119, v119
	v_perm_b32 v114, v115, v114, s58
	v_max_f32_e32 v115, 0x4b000001, v117
	v_max_f32_e32 v116, 0x4b000001, v116
	v_rcp_f32_e32 v120, v120
	v_rcp_f32_e32 v121, v121
	v_perm_b32 v115, v115, v116, s58
	v_pk_fma_f32 v[162:163], v[162:163], s[26:27], v[126:127] op_sel_hi:[1,0,0]
	v_pk_fma_f32 v[194:195], v[194:195], s[26:27], v[126:127] op_sel_hi:[1,0,0]
	v_max_f32_e32 v161, 0x4b000001, v163
	v_max_f32_e32 v162, 0x4b000001, v162
	v_pk_fma_f32 v[118:119], v[118:119], s[26:27], v[126:127] op_sel_hi:[1,0,0]
	v_perm_b32 v161, v161, v162, s58
	v_max_f32_e32 v162, 0x4b000001, v195
	v_max_f32_e32 v163, 0x4b000001, v194
	v_pk_fma_f32 v[120:121], v[120:121], s[26:27], v[126:127] op_sel_hi:[1,0,0]
	v_max_f32_e32 v119, 0x4b000001, v119
	v_max_f32_e32 v118, 0x4b000001, v118
	v_perm_b32 v162, v162, v163, s58
	v_perm_b32 v118, v119, v118, s58
	v_max_f32_e32 v119, 0x4b000001, v121
	v_max_f32_e32 v120, 0x4b000001, v120
	v_lshl_or_b32 v163, v115, 16, v114
	v_perm_b32 v160, v199, v200, s58
	v_perm_b32 v119, v119, v120, s58
	v_lshl_or_b32 v160, v160, 16, v198
	v_lshl_or_b32 v161, v162, 16, v161
	v_lshl_or_b32 v162, v119, 16, v118
	global_store_dwordx4 v[216:217], v[160:163], off
	v_pk_mul_f32 v[98:99], v[130:131], v[98:99]
	v_pk_mul_f32 v[110:111], v[174:175], v[110:111]
	v_pk_mul_f32 v[100:101], v[132:133], v[100:101]
	v_pk_fma_f32 v[98:99], v[98:99], v[188:189], v[128:129] op_sel_hi:[1,0,1]
	v_pk_fma_f32 v[110:111], v[110:111], v[188:189], v[172:173] op_sel_hi:[1,0,1]
	v_pk_fma_f32 v[100:101], v[100:101], v[188:189], v[124:125] op_sel_hi:[1,0,1]
	v_exp_f32_e32 v98, v98
	v_exp_f32_e32 v99, v99
	v_cvt_f32_i32_e32 v113, v113
	v_cvt_f32_i32_e32 v112, v112
	v_exp_f32_e32 v110, v110
	v_exp_f32_e32 v111, v111
	v_cvt_f32_i32_e32 v107, v107
	v_cvt_f32_i32_e32 v106, v106
	v_cvt_f32_i32_e32 v105, v105
	v_cvt_f32_i32_e32 v104, v104
	v_exp_f32_e32 v100, v100
	v_exp_f32_e32 v101, v101
	v_pk_mul_f32 v[108:109], v[168:169], v[108:109]
	v_pk_mul_f32 v[102:103], v[138:139], v[102:103]
	v_pk_add_f32 v[98:99], v[98:99], 1.0 op_sel_hi:[1,0]
	v_pk_mul_f32 v[112:113], v[176:177], v[112:113]
	v_pk_add_f32 v[110:111], v[110:111], 1.0 op_sel_hi:[1,0]
	v_pk_mul_f32 v[106:107], v[166:167], v[106:107]
	v_pk_fma_f32 v[108:109], v[108:109], v[188:189], v[144:145] op_sel_hi:[1,0,1]
	v_pk_mul_f32 v[104:105], v[140:141], v[104:105]
	v_pk_fma_f32 v[102:103], v[102:103], v[188:189], v[136:137] op_sel_hi:[1,0,1]
	v_pk_add_f32 v[100:101], v[100:101], 1.0 op_sel_hi:[1,0]
	v_rcp_f32_e32 v98, v98
	v_rcp_f32_e32 v99, v99
	v_pk_fma_f32 v[112:113], v[112:113], v[188:189], v[170:171] op_sel_hi:[1,0,1]
	v_rcp_f32_e32 v110, v110
	v_rcp_f32_e32 v111, v111
	v_pk_fma_f32 v[106:107], v[106:107], v[188:189], v[164:165] op_sel_hi:[1,0,1]
	v_exp_f32_e32 v108, v108
	v_exp_f32_e32 v109, v109
	v_pk_fma_f32 v[104:105], v[104:105], v[188:189], v[134:135] op_sel_hi:[1,0,1]
	v_exp_f32_e32 v102, v102
	v_exp_f32_e32 v103, v103
	v_rcp_f32_e32 v100, v100
	v_rcp_f32_e32 v101, v101
	v_exp_f32_e32 v112, v112
	v_exp_f32_e32 v113, v113
	v_exp_f32_e32 v106, v106
	v_exp_f32_e32 v107, v107
	v_exp_f32_e32 v104, v104
	v_exp_f32_e32 v105, v105
	v_pk_fma_f32 v[98:99], v[98:99], s[26:27], v[126:127] op_sel_hi:[1,0,0]
	v_pk_fma_f32 v[110:111], v[110:111], s[26:27], v[126:127] op_sel_hi:[1,0,0]
	v_pk_add_f32 v[108:109], v[108:109], 1.0 op_sel_hi:[1,0]
	v_pk_add_f32 v[102:103], v[102:103], 1.0 op_sel_hi:[1,0]
	v_pk_fma_f32 v[100:101], v[100:101], s[26:27], v[126:127] op_sel_hi:[1,0,0]
	v_max_f32_e32 v99, 0x4b000001, v99
	v_max_f32_e32 v98, 0x4b000001, v98
	v_pk_add_f32 v[112:113], v[112:113], 1.0 op_sel_hi:[1,0]
	v_max_f32_e32 v111, 0x4b000001, v111
	v_max_f32_e32 v110, 0x4b000001, v110
	v_pk_add_f32 v[106:107], v[106:107], 1.0 op_sel_hi:[1,0]
	v_rcp_f32_e32 v108, v108
	v_rcp_f32_e32 v109, v109
;     __device__ __forceinline__ void operator()(const f32x4 (&acc)[2][2][4][2], const Unit& u, int wr, int wc, int fr, int fq) const {
;     ...
; #pragma unroll
;         for (int ai = 0; ai < 2; ++ai)
; #pragma unroll
;             for (int m = 0; m < 4; ++m) { unsigned char* rowp = O + (size_t)(row0 + ai * HALF + m * 16) * 8704 + gbase + (col0 & 1023);
;                 const float rs = rsv[ai * 4 + m];
;                 u32x4 w; EPG_Q4(w.x, acc[ai][0][m][0], wv[0][0], rs, bv[0][0]); EPG_Q4(w.y, acc[ai][0][m][1], wv[0][1], rs, bv[0][1]);
;                 EPG_Q4(w.z, acc[ai][1][m][0], wv[1][0], rs, bv[1][0]); EPG_Q4(w.w, acc[ai][1][m][1], wv[1][1], rs, bv[1][1]);
;                 *(u32x4*)rowp = w; }
	v_pk_add_f32 v[104:105], v[104:105], 1.0 op_sel_hi:[1,0]
	v_rcp_f32_e32 v102, v102
	v_rcp_f32_e32 v103, v103
	v_perm_b32 v98, v99, v98, s58
	v_max_f32_e32 v99, 0x4b000001, v101
	v_max_f32_e32 v100, 0x4b000001, v100
	v_rcp_f32_e32 v112, v112
	v_rcp_f32_e32 v113, v113
	v_perm_b32 v116, v111, v110, s58
	v_rcp_f32_e32 v110, v106
	v_rcp_f32_e32 v111, v107
	v_rcp_f32_e32 v104, v104
	v_rcp_f32_e32 v105, v105
	v_perm_b32 v99, v99, v100, s58
	v_pk_fma_f32 v[108:109], v[108:109], s[26:27], v[126:127] op_sel_hi:[1,0,0]
	v_pk_fma_f32 v[102:103], v[102:103], s[26:27], v[126:127] op_sel_hi:[1,0,0]
	v_pk_fma_f32 v[112:113], v[112:113], s[26:27], v[126:127] op_sel_hi:[1,0,0]
	v_pk_fma_f32 v[110:111], v[110:111], s[26:27], v[126:127] op_sel_hi:[1,0,0]
	v_max_f32_e32 v109, 0x4b000001, v109
	v_max_f32_e32 v108, 0x4b000001, v108
	v_pk_fma_f32 v[104:105], v[104:105], s[26:27], v[126:127] op_sel_hi:[1,0,0]
	v_max_f32_e32 v103, 0x4b000001, v103
	v_max_f32_e32 v102, 0x4b000001, v102
	v_mad_i64_i32 v[114:115], s[2:3], v193, s57, v[142:143]
	v_max_f32_e32 v113, 0x4b000001, v113
	v_max_f32_e32 v112, 0x4b000001, v112
	v_max_f32_e32 v107, 0x4b000001, v111
	v_max_f32_e32 v110, 0x4b000001, v110
	v_perm_b32 v108, v109, v108, s58
	v_perm_b32 v102, v103, v102, s58
	v_max_f32_e32 v103, 0x4b000001, v105
	v_max_f32_e32 v104, 0x4b000001, v104
	v_lshl_or_b32 v109, v99, 16, v98
	v_lshl_add_u64 v[114:115], v[114:115], 0, s[0:1]
	v_perm_b32 v106, v113, v112, s58
	v_perm_b32 v107, v107, v110, s58
	v_perm_b32 v103, v103, v104, s58
	v_lshl_add_u64 v[114:115], v[114:115], 0, v[154:155]
	v_lshl_or_b32 v106, v106, 16, v116
	v_lshl_or_b32 v107, v108, 16, v107
	v_lshl_or_b32 v108, v103, 16, v102
	global_store_dwordx4 v[114:115], v[106:109], off
	v_cvt_f32_i32_e32 v92, v92
	v_pk_mul_f32 v[82:83], v[130:131], v[82:83]
	v_pk_mul_f32 v[94:95], v[174:175], v[94:95]
	v_pk_mul_f32 v[84:85], v[132:133], v[84:85]
	v_pk_fma_f32 v[82:83], v[82:83], v[186:187], v[128:129] op_sel_hi:[1,0,1]
	v_pk_fma_f32 v[94:95], v[94:95], v[186:187], v[172:173] op_sel_hi:[1,0,1]
	v_cvt_f32_i32_e32 v87, v87
	v_cvt_f32_i32_e32 v86, v86
	v_pk_fma_f32 v[84:85], v[84:85], v[186:187], v[124:125] op_sel_hi:[1,0,1]
	v_exp_f32_e32 v82, v82
	v_exp_f32_e32 v83, v83
	v_cvt_f32_i32_e32 v97, v97
	v_cvt_f32_i32_e32 v96, v96
	v_exp_f32_e32 v94, v94
	v_exp_f32_e32 v95, v95
	v_cvt_f32_i32_e32 v91, v91
	v_cvt_f32_i32_e32 v90, v90
	v_cvt_f32_i32_e32 v89, v89
	v_cvt_f32_i32_e32 v88, v88
	v_exp_f32_e32 v84, v84
	v_exp_f32_e32 v85, v85
	v_pk_mul_f32 v[92:93], v[168:169], v[92:93]
	v_pk_mul_f32 v[86:87], v[138:139], v[86:87]
	v_pk_add_f32 v[82:83], v[82:83], 1.0 op_sel_hi:[1,0]
	v_pk_mul_f32 v[96:97], v[176:177], v[96:97]
	v_pk_add_f32 v[94:95], v[94:95], 1.0 op_sel_hi:[1,0]
	v_pk_mul_f32 v[90:91], v[166:167], v[90:91]
	v_pk_fma_f32 v[92:93], v[92:93], v[186:187], v[144:145] op_sel_hi:[1,0,1]
	v_pk_mul_f32 v[88:89], v[140:141], v[88:89]
	v_pk_fma_f32 v[86:87], v[86:87], v[186:187], v[136:137] op_sel_hi:[1,0,1]
	v_pk_add_f32 v[84:85], v[84:85], 1.0 op_sel_hi:[1,0]
	v_rcp_f32_e32 v82, v82
	v_rcp_f32_e32 v83, v83
	v_pk_fma_f32 v[96:97], v[96:97], v[186:187], v[170:171] op_sel_hi:[1,0,1]
	v_rcp_f32_e32 v94, v94
	v_rcp_f32_e32 v95, v95
	v_pk_fma_f32 v[90:91], v[90:91], v[186:187], v[164:165] op_sel_hi:[1,0,1]
	v_exp_f32_e32 v92, v92
	v_exp_f32_e32 v93, v93
	v_pk_fma_f32 v[88:89], v[88:89], v[186:187], v[134:135] op_sel_hi:[1,0,1]
	v_exp_f32_e32 v86, v86
	v_exp_f32_e32 v87, v87
	v_rcp_f32_e32 v84, v84
	v_rcp_f32_e32 v85, v85
	v_exp_f32_e32 v96, v96
	v_exp_f32_e32 v97, v97
	v_exp_f32_e32 v90, v90
	v_exp_f32_e32 v91, v91
	v_exp_f32_e32 v88, v88
	v_exp_f32_e32 v89, v89
	v_pk_fma_f32 v[82:83], v[82:83], s[26:27], v[126:127] op_sel_hi:[1,0,0]
	v_pk_fma_f32 v[94:95], v[94:95], s[26:27], v[126:127] op_sel_hi:[1,0,0]
	v_pk_add_f32 v[92:93], v[92:93], 1.0 op_sel_hi:[1,0]
	v_pk_add_f32 v[86:87], v[86:87], 1.0 op_sel_hi:[1,0]
	v_pk_fma_f32 v[84:85], v[84:85], s[26:27], v[126:127] op_sel_hi:[1,0,0]
	v_max_f32_e32 v83, 0x4b000001, v83
	v_max_f32_e32 v82, 0x4b000001, v82
	v_pk_add_f32 v[96:97], v[96:97], 1.0 op_sel_hi:[1,0]
	v_max_f32_e32 v95, 0x4b000001, v95
	v_max_f32_e32 v94, 0x4b000001, v94
	v_pk_add_f32 v[90:91], v[90:91], 1.0 op_sel_hi:[1,0]
	v_rcp_f32_e32 v92, v92
	v_rcp_f32_e32 v93, v93
	v_pk_add_f32 v[88:89], v[88:89], 1.0 op_sel_hi:[1,0]
	v_rcp_f32_e32 v86, v86
	v_rcp_f32_e32 v87, v87
	v_perm_b32 v82, v83, v82, s58
	v_max_f32_e32 v83, 0x4b000001, v85
	v_max_f32_e32 v84, 0x4b000001, v84
	v_rcp_f32_e32 v96, v96
	v_rcp_f32_e32 v97, v97
	v_perm_b32 v100, v95, v94, s58
	v_rcp_f32_e32 v94, v90
	v_rcp_f32_e32 v95, v91
	v_rcp_f32_e32 v88, v88
	v_rcp_f32_e32 v89, v89
	v_perm_b32 v83, v83, v84, s58
	v_pk_fma_f32 v[92:93], v[92:93], s[26:27], v[126:127] op_sel_hi:[1,0,0]
	v_pk_fma_f32 v[86:87], v[86:87], s[26:27], v[126:127] op_sel_hi:[1,0,0]
	v_pk_fma_f32 v[96:97], v[96:97], s[26:27], v[126:127] op_sel_hi:[1,0,0]
	v_pk_fma_f32 v[94:95], v[94:95], s[26:27], v[126:127] op_sel_hi:[1,0,0]
	v_max_f32_e32 v93, 0x4b000001, v93
	v_max_f32_e32 v92, 0x4b000001, v92
	v_pk_fma_f32 v[88:89], v[88:89], s[26:27], v[126:127] op_sel_hi:[1,0,0]
	v_max_f32_e32 v87, 0x4b000001, v87
	v_max_f32_e32 v86, 0x4b000001, v86
	v_mad_i64_i32 v[98:99], s[2:3], v207, s57, v[142:143]
	v_max_f32_e32 v97, 0x4b000001, v97
	v_max_f32_e32 v96, 0x4b000001, v96
	v_max_f32_e32 v91, 0x4b000001, v95
	v_max_f32_e32 v94, 0x4b000001, v94
	v_perm_b32 v92, v93, v92, s58
	v_perm_b32 v86, v87, v86, s58
	v_max_f32_e32 v87, 0x4b000001, v89
	v_max_f32_e32 v88, 0x4b000001, v88
	v_lshl_or_b32 v93, v83, 16, v82
	v_lshl_add_u64 v[98:99], v[98:99], 0, s[0:1]
	v_perm_b32 v90, v97, v96, s58
	v_perm_b32 v91, v91, v94, s58
;     __device__ __forceinline__ void operator()(const f32x4 (&acc)[2][2][4][2], const Unit& u, int wr, int wc, int fr, int fq) const {
;     ...
; #pragma unroll
;         for (int ai = 0; ai < 2; ++ai)
; #pragma unroll
;             for (int m = 0; m < 4; ++m) { unsigned char* rowp = O + (size_t)(row0 + ai * HALF + m * 16) * 8704 + gbase + (col0 & 1023);
;                 const float rs = rsv[ai * 4 + m];
;                 u32x4 w; EPG_Q4(w.x, acc[ai][0][m][0], wv[0][0], rs, bv[0][0]); EPG_Q4(w.y, acc[ai][0][m][1], wv[0][1], rs, bv[0][1]);
;                 EPG_Q4(w.z, acc[ai][1][m][0], wv[1][0], rs, bv[1][0]); EPG_Q4(w.w, acc[ai][1][m][1], wv[1][1], rs, bv[1][1]);
;                 *(u32x4*)rowp = w; }
	v_perm_b32 v87, v87, v88, s58
	v_lshl_add_u64 v[98:99], v[98:99], 0, v[154:155]
	v_lshl_or_b32 v90, v90, 16, v100
	v_lshl_or_b32 v91, v92, 16, v91
	v_lshl_or_b32 v92, v87, 16, v86
	global_store_dwordx4 v[98:99], v[90:93], off
	v_pk_mul_f32 v[66:67], v[130:131], v[66:67]
	v_pk_mul_f32 v[78:79], v[174:175], v[78:79]
	v_pk_mul_f32 v[68:69], v[132:133], v[68:69]
	v_pk_fma_f32 v[66:67], v[66:67], v[184:185], v[128:129] op_sel_hi:[1,0,1]
	v_pk_fma_f32 v[78:79], v[78:79], v[184:185], v[172:173] op_sel_hi:[1,0,1]
	v_cvt_f32_i32_e32 v77, v77
	v_cvt_f32_i32_e32 v76, v76
	v_cvt_f32_i32_e32 v71, v71
	v_cvt_f32_i32_e32 v70, v70
	v_pk_fma_f32 v[68:69], v[68:69], v[184:185], v[124:125] op_sel_hi:[1,0,1]
	v_exp_f32_e32 v66, v66
	v_exp_f32_e32 v67, v67
	v_cvt_f32_i32_e32 v81, v81
	v_cvt_f32_i32_e32 v80, v80
	v_exp_f32_e32 v78, v78
	v_exp_f32_e32 v79, v79
	v_cvt_f32_i32_e32 v75, v75
	v_cvt_f32_i32_e32 v74, v74
	v_cvt_f32_i32_e32 v73, v73
	v_cvt_f32_i32_e32 v72, v72
	v_exp_f32_e32 v68, v68
	v_exp_f32_e32 v69, v69
	v_pk_mul_f32 v[76:77], v[168:169], v[76:77]
	v_pk_mul_f32 v[70:71], v[138:139], v[70:71]
	v_pk_add_f32 v[66:67], v[66:67], 1.0 op_sel_hi:[1,0]
	v_pk_mul_f32 v[80:81], v[176:177], v[80:81]
	v_pk_add_f32 v[78:79], v[78:79], 1.0 op_sel_hi:[1,0]
	v_pk_mul_f32 v[74:75], v[166:167], v[74:75]
	v_pk_fma_f32 v[76:77], v[76:77], v[184:185], v[144:145] op_sel_hi:[1,0,1]
	v_pk_mul_f32 v[72:73], v[140:141], v[72:73]
	v_pk_fma_f32 v[70:71], v[70:71], v[184:185], v[136:137] op_sel_hi:[1,0,1]
	v_pk_add_f32 v[68:69], v[68:69], 1.0 op_sel_hi:[1,0]
	v_rcp_f32_e32 v66, v66
	v_rcp_f32_e32 v67, v67
	v_pk_fma_f32 v[80:81], v[80:81], v[184:185], v[170:171] op_sel_hi:[1,0,1]
	v_rcp_f32_e32 v78, v78
	v_rcp_f32_e32 v79, v79
	v_pk_fma_f32 v[74:75], v[74:75], v[184:185], v[164:165] op_sel_hi:[1,0,1]
	v_exp_f32_e32 v76, v76
	v_exp_f32_e32 v77, v77
	v_pk_fma_f32 v[72:73], v[72:73], v[184:185], v[134:135] op_sel_hi:[1,0,1]
	v_exp_f32_e32 v70, v70
	v_exp_f32_e32 v71, v71
	v_rcp_f32_e32 v68, v68
	v_rcp_f32_e32 v69, v69
	v_exp_f32_e32 v80, v80
	v_exp_f32_e32 v81, v81
	v_exp_f32_e32 v74, v74
	v_exp_f32_e32 v75, v75
	v_exp_f32_e32 v72, v72
	v_exp_f32_e32 v73, v73
	v_pk_fma_f32 v[66:67], v[66:67], s[26:27], v[126:127] op_sel_hi:[1,0,0]
	v_pk_fma_f32 v[78:79], v[78:79], s[26:27], v[126:127] op_sel_hi:[1,0,0]
	v_pk_add_f32 v[76:77], v[76:77], 1.0 op_sel_hi:[1,0]
	v_pk_add_f32 v[70:71], v[70:71], 1.0 op_sel_hi:[1,0]
	v_pk_fma_f32 v[68:69], v[68:69], s[26:27], v[126:127] op_sel_hi:[1,0,0]
	v_max_f32_e32 v67, 0x4b000001, v67
	v_max_f32_e32 v66, 0x4b000001, v66
	v_pk_add_f32 v[80:81], v[80:81], 1.0 op_sel_hi:[1,0]
	v_max_f32_e32 v79, 0x4b000001, v79
	v_max_f32_e32 v78, 0x4b000001, v78
	v_pk_add_f32 v[74:75], v[74:75], 1.0 op_sel_hi:[1,0]
	v_rcp_f32_e32 v76, v76
	v_rcp_f32_e32 v77, v77
	v_pk_add_f32 v[72:73], v[72:73], 1.0 op_sel_hi:[1,0]
	v_rcp_f32_e32 v70, v70
	v_rcp_f32_e32 v71, v71
	v_perm_b32 v66, v67, v66, s58
	v_max_f32_e32 v67, 0x4b000001, v69
	v_max_f32_e32 v68, 0x4b000001, v68
	v_rcp_f32_e32 v80, v80
	v_rcp_f32_e32 v81, v81
	v_perm_b32 v84, v79, v78, s58
	v_rcp_f32_e32 v78, v74
	v_rcp_f32_e32 v79, v75
	v_rcp_f32_e32 v72, v72
	v_rcp_f32_e32 v73, v73
	v_perm_b32 v67, v67, v68, s58
	v_pk_fma_f32 v[76:77], v[76:77], s[26:27], v[126:127] op_sel_hi:[1,0,0]
	v_pk_fma_f32 v[70:71], v[70:71], s[26:27], v[126:127] op_sel_hi:[1,0,0]
	v_pk_fma_f32 v[80:81], v[80:81], s[26:27], v[126:127] op_sel_hi:[1,0,0]
	v_pk_fma_f32 v[78:79], v[78:79], s[26:27], v[126:127] op_sel_hi:[1,0,0]
	v_max_f32_e32 v77, 0x4b000001, v77
	v_max_f32_e32 v76, 0x4b000001, v76
	v_pk_fma_f32 v[72:73], v[72:73], s[26:27], v[126:127] op_sel_hi:[1,0,0]
	v_max_f32_e32 v71, 0x4b000001, v71
	v_max_f32_e32 v70, 0x4b000001, v70
	v_mad_i64_i32 v[82:83], s[2:3], v192, s57, v[142:143]
	v_max_f32_e32 v81, 0x4b000001, v81
	v_max_f32_e32 v80, 0x4b000001, v80
	v_max_f32_e32 v75, 0x4b000001, v79
	v_max_f32_e32 v78, 0x4b000001, v78
	v_perm_b32 v76, v77, v76, s58
	v_perm_b32 v70, v71, v70, s58
	v_max_f32_e32 v71, 0x4b000001, v73
	v_max_f32_e32 v72, 0x4b000001, v72
	v_lshl_or_b32 v77, v67, 16, v66
	v_lshl_add_u64 v[82:83], v[82:83], 0, s[0:1]
	v_perm_b32 v74, v81, v80, s58
	v_perm_b32 v75, v75, v78, s58
	v_perm_b32 v71, v71, v72, s58
	v_lshl_add_u64 v[82:83], v[82:83], 0, v[154:155]
	v_lshl_or_b32 v74, v74, 16, v84
	v_lshl_or_b32 v75, v76, 16, v75
	v_lshl_or_b32 v76, v71, 16, v70
	global_store_dwordx4 v[82:83], v[74:77], off
	v_pk_mul_f32 v[50:51], v[130:131], v[50:51]
	v_pk_mul_f32 v[62:63], v[174:175], v[62:63]
	v_pk_mul_f32 v[52:53], v[132:133], v[52:53]
	v_pk_fma_f32 v[50:51], v[50:51], v[182:183], v[128:129] op_sel_hi:[1,0,1]
	v_pk_fma_f32 v[62:63], v[62:63], v[182:183], v[172:173] op_sel_hi:[1,0,1]
	v_cvt_f32_i32_e32 v61, v61
	v_cvt_f32_i32_e32 v60, v60
	v_cvt_f32_i32_e32 v55, v55
	v_cvt_f32_i32_e32 v54, v54
	v_pk_fma_f32 v[52:53], v[52:53], v[182:183], v[124:125] op_sel_hi:[1,0,1]
	v_exp_f32_e32 v50, v50
	v_exp_f32_e32 v51, v51
	v_cvt_f32_i32_e32 v65, v65
	v_cvt_f32_i32_e32 v64, v64
	v_exp_f32_e32 v62, v62
	v_exp_f32_e32 v63, v63
	v_cvt_f32_i32_e32 v59, v59
	v_cvt_f32_i32_e32 v58, v58
	v_cvt_f32_i32_e32 v57, v57
	v_cvt_f32_i32_e32 v56, v56
	v_exp_f32_e32 v52, v52
	v_exp_f32_e32 v53, v53
	v_pk_mul_f32 v[60:61], v[168:169], v[60:61]
	v_pk_mul_f32 v[54:55], v[138:139], v[54:55]
	v_pk_add_f32 v[50:51], v[50:51], 1.0 op_sel_hi:[1,0]
	v_pk_mul_f32 v[64:65], v[176:177], v[64:65]
	v_pk_add_f32 v[62:63], v[62:63], 1.0 op_sel_hi:[1,0]
	v_pk_mul_f32 v[58:59], v[166:167], v[58:59]
	v_pk_fma_f32 v[60:61], v[60:61], v[182:183], v[144:145] op_sel_hi:[1,0,1]
	v_pk_mul_f32 v[56:57], v[140:141], v[56:57]
	v_pk_fma_f32 v[54:55], v[54:55], v[182:183], v[136:137] op_sel_hi:[1,0,1]
;     __device__ __forceinline__ void operator()(const f32x4 (&acc)[2][2][4][2], const Unit& u, int wr, int wc, int fr, int fq) const {
;     ...
; #pragma unroll
;         for (int ai = 0; ai < 2; ++ai)
; #pragma unroll
;             for (int m = 0; m < 4; ++m) { unsigned char* rowp = O + (size_t)(row0 + ai * HALF + m * 16) * 8704 + gbase + (col0 & 1023);
;                 const float rs = rsv[ai * 4 + m];
;                 u32x4 w; EPG_Q4(w.x, acc[ai][0][m][0], wv[0][0], rs, bv[0][0]); EPG_Q4(w.y, acc[ai][0][m][1], wv[0][1], rs, bv[0][1]);
;                 EPG_Q4(w.z, acc[ai][1][m][0], wv[1][0], rs, bv[1][0]); EPG_Q4(w.w, acc[ai][1][m][1], wv[1][1], rs, bv[1][1]);
;                 *(u32x4*)rowp = w; }
	v_pk_add_f32 v[52:53], v[52:53], 1.0 op_sel_hi:[1,0]
	v_rcp_f32_e32 v50, v50
	v_rcp_f32_e32 v51, v51
	v_pk_fma_f32 v[64:65], v[64:65], v[182:183], v[170:171] op_sel_hi:[1,0,1]
	v_rcp_f32_e32 v62, v62
	v_rcp_f32_e32 v63, v63
	v_pk_fma_f32 v[58:59], v[58:59], v[182:183], v[164:165] op_sel_hi:[1,0,1]
	v_exp_f32_e32 v60, v60
	v_exp_f32_e32 v61, v61
	v_pk_fma_f32 v[56:57], v[56:57], v[182:183], v[134:135] op_sel_hi:[1,0,1]
	v_exp_f32_e32 v54, v54
	v_exp_f32_e32 v55, v55
	v_rcp_f32_e32 v52, v52
	v_rcp_f32_e32 v53, v53
	v_exp_f32_e32 v64, v64
	v_exp_f32_e32 v65, v65
	v_exp_f32_e32 v58, v58
	v_exp_f32_e32 v59, v59
	v_exp_f32_e32 v56, v56
	v_exp_f32_e32 v57, v57
	v_pk_fma_f32 v[50:51], v[50:51], s[26:27], v[126:127] op_sel_hi:[1,0,0]
	v_pk_fma_f32 v[62:63], v[62:63], s[26:27], v[126:127] op_sel_hi:[1,0,0]
	v_pk_add_f32 v[60:61], v[60:61], 1.0 op_sel_hi:[1,0]
	v_pk_add_f32 v[54:55], v[54:55], 1.0 op_sel_hi:[1,0]
	v_pk_fma_f32 v[52:53], v[52:53], s[26:27], v[126:127] op_sel_hi:[1,0,0]
	v_max_f32_e32 v51, 0x4b000001, v51
	v_max_f32_e32 v50, 0x4b000001, v50
	v_pk_add_f32 v[64:65], v[64:65], 1.0 op_sel_hi:[1,0]
	v_max_f32_e32 v63, 0x4b000001, v63
	v_max_f32_e32 v62, 0x4b000001, v62
	v_pk_add_f32 v[58:59], v[58:59], 1.0 op_sel_hi:[1,0]
	v_rcp_f32_e32 v60, v60
	v_rcp_f32_e32 v61, v61
	v_pk_add_f32 v[56:57], v[56:57], 1.0 op_sel_hi:[1,0]
	v_rcp_f32_e32 v54, v54
	v_rcp_f32_e32 v55, v55
	v_perm_b32 v50, v51, v50, s58
	v_max_f32_e32 v51, 0x4b000001, v53
	v_max_f32_e32 v52, 0x4b000001, v52
	v_rcp_f32_e32 v64, v64
	v_rcp_f32_e32 v65, v65
	v_perm_b32 v68, v63, v62, s58
	v_rcp_f32_e32 v62, v58
	v_rcp_f32_e32 v63, v59
	v_rcp_f32_e32 v56, v56
	v_rcp_f32_e32 v57, v57
	v_perm_b32 v51, v51, v52, s58
	v_pk_fma_f32 v[60:61], v[60:61], s[26:27], v[126:127] op_sel_hi:[1,0,0]
	v_pk_fma_f32 v[54:55], v[54:55], s[26:27], v[126:127] op_sel_hi:[1,0,0]
	v_pk_fma_f32 v[64:65], v[64:65], s[26:27], v[126:127] op_sel_hi:[1,0,0]
	v_pk_fma_f32 v[62:63], v[62:63], s[26:27], v[126:127] op_sel_hi:[1,0,0]
	v_max_f32_e32 v61, 0x4b000001, v61
	v_max_f32_e32 v60, 0x4b000001, v60
	v_pk_fma_f32 v[56:57], v[56:57], s[26:27], v[126:127] op_sel_hi:[1,0,0]
	v_max_f32_e32 v55, 0x4b000001, v55
	v_max_f32_e32 v54, 0x4b000001, v54
	v_mad_i64_i32 v[66:67], s[2:3], v191, s57, v[142:143]
	v_max_f32_e32 v65, 0x4b000001, v65
	v_max_f32_e32 v64, 0x4b000001, v64
	v_max_f32_e32 v59, 0x4b000001, v63
	v_max_f32_e32 v62, 0x4b000001, v62
	v_perm_b32 v60, v61, v60, s58
	v_perm_b32 v54, v55, v54, s58
	v_max_f32_e32 v55, 0x4b000001, v57
	v_max_f32_e32 v56, 0x4b000001, v56
	v_lshl_or_b32 v61, v51, 16, v50
	v_lshl_add_u64 v[66:67], v[66:67], 0, s[0:1]
	v_perm_b32 v58, v65, v64, s58
	v_perm_b32 v59, v59, v62, s58
	v_perm_b32 v55, v55, v56, s58
	v_lshl_add_u64 v[66:67], v[66:67], 0, v[154:155]
	v_lshl_or_b32 v58, v58, 16, v68
	v_lshl_or_b32 v59, v60, 16, v59
	v_lshl_or_b32 v60, v55, 16, v54
	global_store_dwordx4 v[66:67], v[58:61], off
	v_pk_mul_f32 v[34:35], v[130:131], v[34:35]
	v_pk_mul_f32 v[46:47], v[174:175], v[46:47]
	v_pk_mul_f32 v[36:37], v[132:133], v[36:37]
	v_pk_fma_f32 v[34:35], v[34:35], v[180:181], v[128:129] op_sel_hi:[1,0,1]
	v_pk_fma_f32 v[46:47], v[46:47], v[180:181], v[172:173] op_sel_hi:[1,0,1]
	v_cvt_f32_i32_e32 v45, v45
	v_cvt_f32_i32_e32 v44, v44
	v_cvt_f32_i32_e32 v39, v39
	v_cvt_f32_i32_e32 v38, v38
	v_pk_fma_f32 v[36:37], v[36:37], v[180:181], v[124:125] op_sel_hi:[1,0,1]
	v_exp_f32_e32 v34, v34
	v_exp_f32_e32 v35, v35
	v_cvt_f32_i32_e32 v49, v49
	v_cvt_f32_i32_e32 v48, v48
	v_exp_f32_e32 v46, v46
	v_exp_f32_e32 v47, v47
	v_cvt_f32_i32_e32 v43, v43
	v_cvt_f32_i32_e32 v42, v42
	v_cvt_f32_i32_e32 v41, v41
	v_cvt_f32_i32_e32 v40, v40
	v_exp_f32_e32 v36, v36
	v_exp_f32_e32 v37, v37
	v_pk_mul_f32 v[44:45], v[168:169], v[44:45]
	v_pk_mul_f32 v[38:39], v[138:139], v[38:39]
	v_pk_add_f32 v[34:35], v[34:35], 1.0 op_sel_hi:[1,0]
	v_pk_mul_f32 v[48:49], v[176:177], v[48:49]
	v_pk_add_f32 v[46:47], v[46:47], 1.0 op_sel_hi:[1,0]
	v_pk_mul_f32 v[42:43], v[166:167], v[42:43]
	v_pk_fma_f32 v[44:45], v[44:45], v[180:181], v[144:145] op_sel_hi:[1,0,1]
	v_pk_mul_f32 v[40:41], v[140:141], v[40:41]
	v_pk_fma_f32 v[38:39], v[38:39], v[180:181], v[136:137] op_sel_hi:[1,0,1]
	v_pk_add_f32 v[36:37], v[36:37], 1.0 op_sel_hi:[1,0]
	v_rcp_f32_e32 v34, v34
	v_rcp_f32_e32 v35, v35
	v_pk_fma_f32 v[48:49], v[48:49], v[180:181], v[170:171] op_sel_hi:[1,0,1]
	v_rcp_f32_e32 v46, v46
	v_rcp_f32_e32 v47, v47
	v_pk_fma_f32 v[42:43], v[42:43], v[180:181], v[164:165] op_sel_hi:[1,0,1]
	v_exp_f32_e32 v44, v44
	v_exp_f32_e32 v45, v45
	v_pk_fma_f32 v[40:41], v[40:41], v[180:181], v[134:135] op_sel_hi:[1,0,1]
	v_exp_f32_e32 v38, v38
	v_exp_f32_e32 v39, v39
	v_rcp_f32_e32 v36, v36
	v_rcp_f32_e32 v37, v37
	v_exp_f32_e32 v48, v48
	v_exp_f32_e32 v49, v49
	v_exp_f32_e32 v42, v42
	v_exp_f32_e32 v43, v43
	v_exp_f32_e32 v40, v40
	v_exp_f32_e32 v41, v41
	v_pk_fma_f32 v[34:35], v[34:35], s[26:27], v[126:127] op_sel_hi:[1,0,0]
	v_pk_fma_f32 v[46:47], v[46:47], s[26:27], v[126:127] op_sel_hi:[1,0,0]
	v_pk_add_f32 v[44:45], v[44:45], 1.0 op_sel_hi:[1,0]
	v_pk_add_f32 v[38:39], v[38:39], 1.0 op_sel_hi:[1,0]
	v_pk_fma_f32 v[36:37], v[36:37], s[26:27], v[126:127] op_sel_hi:[1,0,0]
	v_max_f32_e32 v35, 0x4b000001, v35
	v_max_f32_e32 v34, 0x4b000001, v34
	v_pk_add_f32 v[48:49], v[48:49], 1.0 op_sel_hi:[1,0]
	v_max_f32_e32 v47, 0x4b000001, v47
	v_max_f32_e32 v46, 0x4b000001, v46
	v_pk_add_f32 v[42:43], v[42:43], 1.0 op_sel_hi:[1,0]
	v_rcp_f32_e32 v44, v44
	v_rcp_f32_e32 v45, v45
	v_pk_add_f32 v[40:41], v[40:41], 1.0 op_sel_hi:[1,0]
	v_rcp_f32_e32 v38, v38
	v_rcp_f32_e32 v39, v39
	v_perm_b32 v34, v35, v34, s58
	v_max_f32_e32 v35, 0x4b000001, v37
;     __device__ __forceinline__ void operator()(const f32x4 (&acc)[2][2][4][2], const Unit& u, int wr, int wc, int fr, int fq) const {
;     ...
; #pragma unroll
;         for (int ai = 0; ai < 2; ++ai)
; #pragma unroll
;             for (int m = 0; m < 4; ++m) { unsigned char* rowp = O + (size_t)(row0 + ai * HALF + m * 16) * 8704 + gbase + (col0 & 1023);
;                 const float rs = rsv[ai * 4 + m];
;                 u32x4 w; EPG_Q4(w.x, acc[ai][0][m][0], wv[0][0], rs, bv[0][0]); EPG_Q4(w.y, acc[ai][0][m][1], wv[0][1], rs, bv[0][1]);
;                 EPG_Q4(w.z, acc[ai][1][m][0], wv[1][0], rs, bv[1][0]); EPG_Q4(w.w, acc[ai][1][m][1], wv[1][1], rs, bv[1][1]);
;                 *(u32x4*)rowp = w; }
	v_max_f32_e32 v36, 0x4b000001, v36
	v_rcp_f32_e32 v48, v48
	v_rcp_f32_e32 v49, v49
	v_perm_b32 v52, v47, v46, s58
	v_rcp_f32_e32 v46, v42
	v_rcp_f32_e32 v47, v43
	v_rcp_f32_e32 v40, v40
	v_rcp_f32_e32 v41, v41
	v_perm_b32 v35, v35, v36, s58
	v_pk_fma_f32 v[44:45], v[44:45], s[26:27], v[126:127] op_sel_hi:[1,0,0]
	v_pk_fma_f32 v[38:39], v[38:39], s[26:27], v[126:127] op_sel_hi:[1,0,0]
	v_pk_fma_f32 v[48:49], v[48:49], s[26:27], v[126:127] op_sel_hi:[1,0,0]
	v_pk_fma_f32 v[46:47], v[46:47], s[26:27], v[126:127] op_sel_hi:[1,0,0]
	v_max_f32_e32 v45, 0x4b000001, v45
	v_max_f32_e32 v44, 0x4b000001, v44
	v_pk_fma_f32 v[40:41], v[40:41], s[26:27], v[126:127] op_sel_hi:[1,0,0]
	v_max_f32_e32 v39, 0x4b000001, v39
	v_max_f32_e32 v38, 0x4b000001, v38
	v_mad_i64_i32 v[50:51], s[2:3], v190, s57, v[142:143]
	v_max_f32_e32 v49, 0x4b000001, v49
	v_max_f32_e32 v48, 0x4b000001, v48
	v_max_f32_e32 v43, 0x4b000001, v47
	v_max_f32_e32 v46, 0x4b000001, v46
	v_perm_b32 v44, v45, v44, s58
	v_perm_b32 v38, v39, v38, s58
	v_max_f32_e32 v39, 0x4b000001, v41
	v_max_f32_e32 v40, 0x4b000001, v40
	v_lshl_or_b32 v45, v35, 16, v34
	v_lshl_add_u64 v[50:51], v[50:51], 0, s[0:1]
	v_perm_b32 v42, v49, v48, s58
	v_perm_b32 v43, v43, v46, s58
	v_perm_b32 v39, v39, v40, s58
	v_lshl_add_u64 v[50:51], v[50:51], 0, v[154:155]
	v_lshl_or_b32 v42, v42, 16, v52
	v_lshl_or_b32 v43, v44, 16, v43
	v_lshl_or_b32 v44, v39, 16, v38
	global_store_dwordx4 v[50:51], v[42:45], off
	v_pk_mul_f32 v[18:19], v[130:131], v[18:19]
	v_pk_mul_f32 v[30:31], v[174:175], v[30:31]
	v_pk_mul_f32 v[20:21], v[132:133], v[20:21]
	v_pk_fma_f32 v[18:19], v[18:19], v[178:179], v[128:129] op_sel_hi:[1,0,1]
	v_pk_fma_f32 v[30:31], v[30:31], v[178:179], v[172:173] op_sel_hi:[1,0,1]
	v_cvt_f32_i32_e32 v29, v29
	v_cvt_f32_i32_e32 v28, v28
	v_cvt_f32_i32_e32 v23, v23
	v_cvt_f32_i32_e32 v22, v22
	v_pk_fma_f32 v[20:21], v[20:21], v[178:179], v[124:125] op_sel_hi:[1,0,1]
	v_exp_f32_e32 v18, v18
	v_exp_f32_e32 v19, v19
	v_cvt_f32_i32_e32 v33, v33
	v_cvt_f32_i32_e32 v32, v32
	v_exp_f32_e32 v30, v30
	v_exp_f32_e32 v31, v31
	v_cvt_f32_i32_e32 v27, v27
	v_cvt_f32_i32_e32 v26, v26
	v_cvt_f32_i32_e32 v25, v25
	v_cvt_f32_i32_e32 v24, v24
	v_exp_f32_e32 v20, v20
	v_exp_f32_e32 v21, v21
	v_pk_mul_f32 v[28:29], v[168:169], v[28:29]
	v_pk_mul_f32 v[22:23], v[138:139], v[22:23]
	v_pk_add_f32 v[18:19], v[18:19], 1.0 op_sel_hi:[1,0]
	v_pk_mul_f32 v[32:33], v[176:177], v[32:33]
	v_pk_add_f32 v[30:31], v[30:31], 1.0 op_sel_hi:[1,0]
	v_pk_mul_f32 v[26:27], v[166:167], v[26:27]
	v_pk_fma_f32 v[28:29], v[28:29], v[178:179], v[144:145] op_sel_hi:[1,0,1]
	v_pk_mul_f32 v[24:25], v[140:141], v[24:25]
	v_pk_fma_f32 v[22:23], v[22:23], v[178:179], v[136:137] op_sel_hi:[1,0,1]
	v_pk_add_f32 v[20:21], v[20:21], 1.0 op_sel_hi:[1,0]
	v_rcp_f32_e32 v18, v18
	v_rcp_f32_e32 v19, v19
	v_pk_fma_f32 v[32:33], v[32:33], v[178:179], v[170:171] op_sel_hi:[1,0,1]
	v_rcp_f32_e32 v30, v30
	v_rcp_f32_e32 v31, v31
	v_pk_fma_f32 v[26:27], v[26:27], v[178:179], v[164:165] op_sel_hi:[1,0,1]
	v_exp_f32_e32 v28, v28
	v_exp_f32_e32 v29, v29
	v_pk_fma_f32 v[24:25], v[24:25], v[178:179], v[134:135] op_sel_hi:[1,0,1]
	v_exp_f32_e32 v22, v22
	v_exp_f32_e32 v23, v23
	v_rcp_f32_e32 v20, v20
	v_rcp_f32_e32 v21, v21
	v_exp_f32_e32 v32, v32
	v_exp_f32_e32 v33, v33
	v_exp_f32_e32 v26, v26
	v_exp_f32_e32 v27, v27
	v_exp_f32_e32 v24, v24
	v_exp_f32_e32 v25, v25
	v_pk_fma_f32 v[18:19], v[18:19], s[26:27], v[126:127] op_sel_hi:[1,0,0]
	v_pk_fma_f32 v[30:31], v[30:31], s[26:27], v[126:127] op_sel_hi:[1,0,0]
	v_pk_add_f32 v[28:29], v[28:29], 1.0 op_sel_hi:[1,0]
	v_pk_add_f32 v[22:23], v[22:23], 1.0 op_sel_hi:[1,0]
	v_pk_fma_f32 v[20:21], v[20:21], s[26:27], v[126:127] op_sel_hi:[1,0,0]
	v_max_f32_e32 v19, 0x4b000001, v19
	v_max_f32_e32 v18, 0x4b000001, v18
	v_pk_add_f32 v[32:33], v[32:33], 1.0 op_sel_hi:[1,0]
	v_max_f32_e32 v31, 0x4b000001, v31
	v_max_f32_e32 v30, 0x4b000001, v30
	v_pk_add_f32 v[26:27], v[26:27], 1.0 op_sel_hi:[1,0]
	v_rcp_f32_e32 v28, v28
	v_rcp_f32_e32 v29, v29
	v_pk_add_f32 v[24:25], v[24:25], 1.0 op_sel_hi:[1,0]
	v_rcp_f32_e32 v22, v22
	v_rcp_f32_e32 v23, v23
	v_perm_b32 v18, v19, v18, s58
	v_max_f32_e32 v19, 0x4b000001, v21
	v_max_f32_e32 v20, 0x4b000001, v20
	v_rcp_f32_e32 v32, v32
	v_rcp_f32_e32 v33, v33
	v_perm_b32 v36, v31, v30, s58
	v_rcp_f32_e32 v30, v26
	v_rcp_f32_e32 v31, v27
	v_rcp_f32_e32 v24, v24
	v_rcp_f32_e32 v25, v25
	v_perm_b32 v19, v19, v20, s58
	v_pk_fma_f32 v[28:29], v[28:29], s[26:27], v[126:127] op_sel_hi:[1,0,0]
	v_pk_fma_f32 v[22:23], v[22:23], s[26:27], v[126:127] op_sel_hi:[1,0,0]
	v_pk_fma_f32 v[32:33], v[32:33], s[26:27], v[126:127] op_sel_hi:[1,0,0]
	v_pk_fma_f32 v[30:31], v[30:31], s[26:27], v[126:127] op_sel_hi:[1,0,0]
	v_max_f32_e32 v29, 0x4b000001, v29
	v_max_f32_e32 v28, 0x4b000001, v28
	v_pk_fma_f32 v[24:25], v[24:25], s[26:27], v[126:127] op_sel_hi:[1,0,0]
	v_max_f32_e32 v23, 0x4b000001, v23
	v_max_f32_e32 v22, 0x4b000001, v22
	v_mad_i64_i32 v[34:35], s[2:3], v189, s57, v[142:143]
;     __device__ __forceinline__ void operator()(const f32x4 (&acc)[2][2][4][2], const Unit& u, int wr, int wc, int fr, int fq) const {
;     ...
; #pragma unroll
;         for (int ai = 0; ai < 2; ++ai)
; #pragma unroll
;             for (int m = 0; m < 4; ++m) { unsigned char* rowp = O + (size_t)(row0 + ai * HALF + m * 16) * 8704 + gbase + (col0 & 1023);
;                 const float rs = rsv[ai * 4 + m];
;                 u32x4 w; EPG_Q4(w.x, acc[ai][0][m][0], wv[0][0], rs, bv[0][0]); EPG_Q4(w.y, acc[ai][0][m][1], wv[0][1], rs, bv[0][1]);
;                 EPG_Q4(w.z, acc[ai][1][m][0], wv[1][0], rs, bv[1][0]); EPG_Q4(w.w, acc[ai][1][m][1], wv[1][1], rs, bv[1][1]);
;                 *(u32x4*)rowp = w; }
	v_max_f32_e32 v33, 0x4b000001, v33
	v_max_f32_e32 v32, 0x4b000001, v32
	v_max_f32_e32 v27, 0x4b000001, v31
	v_max_f32_e32 v30, 0x4b000001, v30
	v_perm_b32 v28, v29, v28, s58
	v_perm_b32 v22, v23, v22, s58
	v_max_f32_e32 v23, 0x4b000001, v25
	v_max_f32_e32 v24, 0x4b000001, v24
	v_lshl_or_b32 v29, v19, 16, v18
	v_lshl_add_u64 v[34:35], v[34:35], 0, s[0:1]
	v_perm_b32 v26, v33, v32, s58
	v_perm_b32 v27, v27, v30, s58
	v_perm_b32 v23, v23, v24, s58
	v_lshl_add_u64 v[34:35], v[34:35], 0, v[154:155]
	v_lshl_or_b32 v26, v26, 16, v36
	v_lshl_or_b32 v27, v28, 16, v27
	v_lshl_or_b32 v28, v23, 16, v22
	global_store_dwordx4 v[34:35], v[26:29], off
	v_pk_mul_f32 v[14:15], v[174:175], v[14:15]
	v_pk_fma_f32 v[14:15], v[14:15], v[122:123], v[172:173] op_sel_hi:[1,0,1]
	v_cvt_f32_i32_e32 v7, v7
	v_cvt_f32_i32_e32 v6, v6
	v_cvt_f32_i32_e32 v3, v3
	v_cvt_f32_i32_e32 v2, v2
	v_cvt_f32_i32_e32 v17, v17
	v_cvt_f32_i32_e32 v16, v16
	v_exp_f32_e32 v14, v14
	v_exp_f32_e32 v15, v15
	v_cvt_f32_i32_e32 v11, v11
	v_cvt_f32_i32_e32 v13, v13
	v_cvt_f32_i32_e32 v12, v12
	v_cvt_f32_i32_e32 v10, v10
	v_cvt_f32_i32_e32 v9, v9
	v_cvt_f32_i32_e32 v8, v8
	v_cvt_f32_i32_e32 v5, v5
	v_cvt_f32_i32_e32 v4, v4
	v_pk_mul_f32 v[6:7], v[138:139], v[6:7]
	v_pk_mul_f32 v[2:3], v[130:131], v[2:3]
	v_pk_mul_f32 v[16:17], v[176:177], v[16:17]
	v_pk_add_f32 v[14:15], v[14:15], 1.0 op_sel_hi:[1,0]
	v_pk_mul_f32 v[12:13], v[168:169], v[12:13]
	v_pk_mul_f32 v[10:11], v[166:167], v[10:11]
	v_pk_mul_f32 v[8:9], v[140:141], v[8:9]
	v_pk_fma_f32 v[6:7], v[6:7], v[122:123], v[136:137] op_sel_hi:[1,0,1]
	v_pk_mul_f32 v[4:5], v[132:133], v[4:5]
	v_pk_fma_f32 v[2:3], v[2:3], v[122:123], v[128:129] op_sel_hi:[1,0,1]
	v_pk_fma_f32 v[16:17], v[16:17], v[122:123], v[170:171] op_sel_hi:[1,0,1]
	v_rcp_f32_e32 v14, v14
	v_rcp_f32_e32 v15, v15
	v_pk_fma_f32 v[12:13], v[12:13], v[122:123], v[144:145] op_sel_hi:[1,0,1]
	v_pk_fma_f32 v[10:11], v[10:11], v[122:123], v[164:165] op_sel_hi:[1,0,1]
	v_pk_fma_f32 v[8:9], v[8:9], v[122:123], v[134:135] op_sel_hi:[1,0,1]
	v_exp_f32_e32 v6, v6
	v_exp_f32_e32 v7, v7
	v_pk_fma_f32 v[4:5], v[4:5], v[122:123], v[124:125] op_sel_hi:[1,0,1]
	v_exp_f32_e32 v2, v2
	v_exp_f32_e32 v3, v3
	v_exp_f32_e32 v16, v16
	v_exp_f32_e32 v17, v17
	v_exp_f32_e32 v10, v10
	v_exp_f32_e32 v12, v12
	v_exp_f32_e32 v13, v13
	v_exp_f32_e32 v11, v11
	v_exp_f32_e32 v8, v8
	v_exp_f32_e32 v9, v9
	v_exp_f32_e32 v4, v4
	v_exp_f32_e32 v5, v5
	v_pk_fma_f32 v[14:15], v[14:15], s[26:27], v[126:127] op_sel_hi:[1,0,0]
	v_pk_add_f32 v[6:7], v[6:7], 1.0 op_sel_hi:[1,0]
	v_pk_add_f32 v[2:3], v[2:3], 1.0 op_sel_hi:[1,0]
	v_pk_add_f32 v[16:17], v[16:17], 1.0 op_sel_hi:[1,0]
	v_max_f32_e32 v15, 0x4b000001, v15
	v_max_f32_e32 v14, 0x4b000001, v14
	v_pk_add_f32 v[12:13], v[12:13], 1.0 op_sel_hi:[1,0]
	v_pk_add_f32 v[10:11], v[10:11], 1.0 op_sel_hi:[1,0]
	v_pk_add_f32 v[8:9], v[8:9], 1.0 op_sel_hi:[1,0]
	v_rcp_f32_e32 v6, v6
	v_rcp_f32_e32 v7, v7
	v_pk_add_f32 v[4:5], v[4:5], 1.0 op_sel_hi:[1,0]
	v_rcp_f32_e32 v2, v2
	v_rcp_f32_e32 v3, v3
	v_rcp_f32_e32 v16, v16
	v_rcp_f32_e32 v17, v17
	v_perm_b32 v20, v15, v14, s58
	v_rcp_f32_e32 v14, v10
	v_rcp_f32_e32 v12, v12
	v_rcp_f32_e32 v13, v13
	v_rcp_f32_e32 v15, v11
	v_rcp_f32_e32 v8, v8
	v_rcp_f32_e32 v9, v9
	v_rcp_f32_e32 v4, v4
	v_rcp_f32_e32 v5, v5
	v_pk_fma_f32 v[6:7], v[6:7], s[26:27], v[126:127] op_sel_hi:[1,0,0]
	v_pk_fma_f32 v[2:3], v[2:3], s[26:27], v[126:127] op_sel_hi:[1,0,0]
	v_pk_fma_f32 v[16:17], v[16:17], s[26:27], v[126:127] op_sel_hi:[1,0,0]
	v_pk_fma_f32 v[12:13], v[12:13], s[26:27], v[126:127] op_sel_hi:[1,0,0]
	v_pk_fma_f32 v[14:15], v[14:15], s[26:27], v[126:127] op_sel_hi:[1,0,0]
	v_pk_fma_f32 v[8:9], v[8:9], s[26:27], v[126:127] op_sel_hi:[1,0,0]
	v_max_f32_e32 v7, 0x4b000001, v7
	v_max_f32_e32 v6, 0x4b000001, v6
	v_pk_fma_f32 v[4:5], v[4:5], s[26:27], v[126:127] op_sel_hi:[1,0,0]
	v_max_f32_e32 v3, 0x4b000001, v3
	v_max_f32_e32 v2, 0x4b000001, v2
	v_mad_i64_i32 v[18:19], s[2:3], v123, s57, v[142:143]
	v_max_f32_e32 v17, 0x4b000001, v17
	v_max_f32_e32 v16, 0x4b000001, v16
	v_max_f32_e32 v11, 0x4b000001, v15
	v_max_f32_e32 v14, 0x4b000001, v14
	v_max_f32_e32 v13, 0x4b000001, v13
	v_max_f32_e32 v12, 0x4b000001, v12
	v_perm_b32 v6, v7, v6, s58
	v_max_f32_e32 v7, 0x4b000001, v9
	v_max_f32_e32 v8, 0x4b000001, v8
	v_perm_b32 v2, v3, v2, s58
	v_max_f32_e32 v3, 0x4b000001, v5
	v_max_f32_e32 v4, 0x4b000001, v4
	v_lshl_add_u64 v[18:19], v[18:19], 0, s[0:1]
	v_perm_b32 v10, v17, v16, s58
	v_perm_b32 v11, v11, v14, s58
	v_perm_b32 v12, v13, v12, s58
	v_perm_b32 v7, v7, v8, s58
	v_perm_b32 v3, v3, v4, s58
	v_lshl_add_u64 v[18:19], v[18:19], 0, v[154:155]
	v_lshl_or_b32 v10, v10, 16, v20
	v_lshl_or_b32 v11, v12, 16, v11
	v_lshl_or_b32 v12, v7, 16, v6
	v_lshl_or_b32 v13, v3, 16, v2
	global_store_dwordx4 v[18:19], v[10:13], off
	s_andn2_b64 vcc, exec, s[4:5]
	s_mov_b64 s[0:1], -1
	s_cbranch_vccnz .LBB0_2544
	s_andn2_b64 vcc, exec, s[6:7]
	s_cbranch_vccnz .LBB0_2543
	s_barrier
	s_branch .LBB0_2543
